# SSM scans: drop 72 redundant v_mov lane shuffles (use op_sel high-dword select in v_pk_fma_f32), bit-identical
# speedup vs baseline: 1.0027x; 1.0010x over previous
; #define LAS __attribute__((address_space(3)))
; DI unsigned f2bf(float f) { unsigned u = __builtin_bit_cast(unsigned, f); return (u + 0x7fffu + ((u >> 16) & 1u)) >> 16; }
; DI void ssm_step_lds(const SsmC& c, const LAS bf16_t* up_, float& xr, float& xi) {
;     const LAS f32x4* up = (const LAS f32x4*)up_;
;     const f32x4 u0 = up[0], u1 = up[1], u2 = up[2], u3 = up[3];
;     float sr = 0.f, si = 0.f;
; #pragma unroll
;     for (int e = 0; e < 4; ++e) { sr += c.bbr[e] * u0[e]; si += c.bbi[e] * u0[e]; }
; #pragma unroll
;     for (int e = 0; e < 4; ++e) { sr += c.bbr[4 + e] * u1[e]; si += c.bbi[4 + e] * u1[e]; }
; #pragma unroll
;     for (int e = 0; e < 4; ++e) { sr += c.bbr[8 + e] * u2[e]; si += c.bbi[8 + e] * u2[e]; }
; #pragma unroll
;     for (int e = 0; e < 4; ++e) { sr += c.bbr[12 + e] * u3[e]; si += c.bbi[12 + e] * u3[e]; }
;     const float nxr = c.ar * xr - c.ai * xi + sr, nxi = c.ar * xi + c.ai * xr + si; xr = nxr; xi = nxi;
; }
; DI void ssm_s3(CArgs& a, int l, int it, int lane, LAS bf16_t* Xs  , LAS bf16_t* Us) {
;     ...
;     for (int sub = 0; sub < 4; ++sub) {
; #pragma unroll 4
;         for (int tt = 0; tt < 32; ++tt) { ssm_step_lds(c, Us + (32 * sub + tt) * 32, xr, xi);
;             Xs[tt * 136 + lane] = (bf16_t)f2bf(xr); Xs[tt * 136 + 64 + lane] = (bf16_t)f2bf(xi); }
.LBB0_180:
	s_add_i32 s4, s0, s3
	s_add_i32 s5, s4, 0x11800
	v_mov_b32_e32 v4, s5
	ds_read_b128 v[42:45], v4
	s_add_i32 s5, s4, 0x11810
	v_mov_b32_e32 v4, s5
	s_add_i32 s5, s4, 0x11820
	ds_read_b128 v[46:49], v4
	v_mov_b32_e32 v4, s5
	s_add_i32 s5, s4, 0x11830
	ds_read_b128 v[50:53], v4
	v_mov_b32_e32 v4, s5
	ds_read_b128 v[128:131], v4
	s_waitcnt lgkmcnt(3)
	v_pk_fma_f32 v[4:5], v[74:75], v[42:43], 0 op_sel_hi:[1,0,0]
	s_add_i32 s5, s4, 0x11840
	v_pk_fma_f32 v[4:5], v[76:77], v[42:43], v[4:5] op_sel:[0,1,0]
	v_mov_b32_e32 v42, v45
	v_pk_fma_f32 v[4:5], v[78:79], v[44:45], v[4:5] op_sel_hi:[1,0,1]
	s_waitcnt lgkmcnt(0)
	v_mov_b32_e32 v44, v131
	v_pk_fma_f32 v[4:5], v[98:99], v[42:43], v[4:5] op_sel_hi:[1,0,1]
	v_pk_fma_f32 v[4:5], v[100:101], v[46:47], v[4:5] op_sel_hi:[1,0,1]
	s_addk_i32 s3, 0x100
	v_pk_fma_f32 v[4:5], v[102:103], v[46:47], v[4:5] op_sel:[0,1,0]
	s_nop 0
	v_pk_fma_f32 v[4:5], v[104:105], v[48:49], v[4:5] op_sel_hi:[1,0,1]
	s_nop 0
	v_pk_fma_f32 v[4:5], v[106:107], v[48:49], v[4:5] op_sel:[0,1,0]
	v_pk_fma_f32 v[4:5], v[108:109], v[50:51], v[4:5] op_sel_hi:[1,0,1]
	s_nop 0
	v_pk_fma_f32 v[4:5], v[110:111], v[50:51], v[4:5] op_sel:[0,1,0]
	s_nop 0
	v_pk_fma_f32 v[4:5], v[112:113], v[52:53], v[4:5] op_sel_hi:[1,0,1]
	s_nop 0
	v_pk_fma_f32 v[4:5], v[114:115], v[52:53], v[4:5] op_sel:[0,1,0]
	v_pk_mul_f32 v[42:43], v[72:73], v[38:39]
	v_pk_fma_f32 v[4:5], v[116:117], v[128:129], v[4:5] op_sel_hi:[1,0,1]
	s_nop 0
	v_pk_fma_f32 v[4:5], v[118:119], v[128:129], v[4:5] op_sel:[0,1,0]
	s_nop 0
	v_pk_fma_f32 v[4:5], v[120:121], v[130:131], v[4:5] op_sel_hi:[1,0,1]
	s_nop 0
	v_pk_fma_f32 v[4:5], v[122:123], v[44:45], v[4:5] op_sel_hi:[1,0,1]
	v_pk_fma_f32 v[44:45], v[70:71], v[38:39], v[42:43] op_sel:[0,0,1] op_sel_hi:[1,1,0]
	v_pk_fma_f32 v[38:39], v[70:71], v[38:39], v[42:43] op_sel:[0,0,1] op_sel_hi:[1,1,0] neg_lo:[0,0,1] neg_hi:[0,0,1]
	s_nop 0
	v_mov_b32_e32 v45, v39
	v_pk_add_f32 v[4:5], v[44:45], v[4:5]
	s_nop 0
	v_bfe_u32 v38, v5, 16, 1
	v_add3_u32 v38, v5, v38, s33
	ds_write_b16_d16_hi v40, v38
	v_bfe_u32 v38, v4, 16, 1
	v_add3_u32 v38, v4, v38, s33
	ds_write_b16_d16_hi v40, v38 offset:128
	v_mov_b32_e32 v38, s5
	ds_read_b128 v[42:45], v38
	s_add_i32 s5, s4, 0x11850
	v_mov_b32_e32 v38, s5
	s_add_i32 s5, s4, 0x11860
	ds_read_b128 v[46:49], v38
	v_mov_b32_e32 v38, s5
	s_add_i32 s5, s4, 0x11870
	ds_read_b128 v[50:53], v38
	v_mov_b32_e32 v38, s5
	ds_read_b128 v[128:131], v38
	s_waitcnt lgkmcnt(3)
	v_pk_fma_f32 v[38:39], v[74:75], v[42:43], 0 op_sel_hi:[1,0,0]
	s_add_i32 s5, s4, 0x11880
	v_pk_fma_f32 v[38:39], v[76:77], v[42:43], v[38:39] op_sel:[0,1,0]
	v_mov_b32_e32 v42, v45
	v_pk_fma_f32 v[38:39], v[78:79], v[44:45], v[38:39] op_sel_hi:[1,0,1]
	s_waitcnt lgkmcnt(0)
	v_mov_b32_e32 v44, v131
	v_pk_fma_f32 v[38:39], v[98:99], v[42:43], v[38:39] op_sel_hi:[1,0,1]
	v_pk_fma_f32 v[38:39], v[100:101], v[46:47], v[38:39] op_sel_hi:[1,0,1]
	s_nop 0
	v_pk_fma_f32 v[38:39], v[102:103], v[46:47], v[38:39] op_sel:[0,1,0]
	s_nop 0
	v_pk_fma_f32 v[38:39], v[104:105], v[48:49], v[38:39] op_sel_hi:[1,0,1]
	s_nop 0
	v_pk_fma_f32 v[38:39], v[106:107], v[48:49], v[38:39] op_sel:[0,1,0]
	v_pk_fma_f32 v[38:39], v[108:109], v[50:51], v[38:39] op_sel_hi:[1,0,1]
	s_nop 0
	v_pk_fma_f32 v[38:39], v[110:111], v[50:51], v[38:39] op_sel:[0,1,0]
	s_nop 0
	v_pk_fma_f32 v[38:39], v[112:113], v[52:53], v[38:39] op_sel_hi:[1,0,1]
	s_nop 0
	v_pk_fma_f32 v[38:39], v[114:115], v[52:53], v[38:39] op_sel:[0,1,0]
	v_pk_mul_f32 v[42:43], v[72:73], v[4:5]
	v_pk_fma_f32 v[38:39], v[116:117], v[128:129], v[38:39] op_sel_hi:[1,0,1]
	s_nop 0
	v_pk_fma_f32 v[38:39], v[118:119], v[128:129], v[38:39] op_sel:[0,1,0]
	s_nop 0
	v_pk_fma_f32 v[38:39], v[120:121], v[130:131], v[38:39] op_sel_hi:[1,0,1]
	s_nop 0
	v_pk_fma_f32 v[38:39], v[122:123], v[44:45], v[38:39] op_sel_hi:[1,0,1]
	v_pk_fma_f32 v[44:45], v[70:71], v[4:5], v[42:43] op_sel:[0,0,1] op_sel_hi:[1,1,0]
	v_pk_fma_f32 v[4:5], v[70:71], v[4:5], v[42:43] op_sel:[0,0,1] op_sel_hi:[1,1,0] neg_lo:[0,0,1] neg_hi:[0,0,1]
	s_nop 0
	v_mov_b32_e32 v45, v5
	v_pk_add_f32 v[4:5], v[44:45], v[38:39]
	s_nop 0
	v_bfe_u32 v38, v5, 16, 1
	v_add3_u32 v38, v5, v38, s33
	ds_write_b16_d16_hi v40, v38 offset:272
	v_bfe_u32 v38, v4, 16, 1
	v_add3_u32 v38, v4, v38, s33
	ds_write_b16_d16_hi v40, v38 offset:400
	v_mov_b32_e32 v38, s5
	ds_read_b128 v[42:45], v38
	s_add_i32 s5, s4, 0x11890
	v_mov_b32_e32 v38, s5
	s_add_i32 s5, s4, 0x118a0
	ds_read_b128 v[46:49], v38
	v_mov_b32_e32 v38, s5
	s_add_i32 s5, s4, 0x118b0
	ds_read_b128 v[50:53], v38
	v_mov_b32_e32 v38, s5
	ds_read_b128 v[128:131], v38
	s_waitcnt lgkmcnt(3)
	v_pk_fma_f32 v[38:39], v[74:75], v[42:43], 0 op_sel_hi:[1,0,0]
	s_add_i32 s5, s4, 0x118c0
	v_pk_fma_f32 v[38:39], v[76:77], v[42:43], v[38:39] op_sel:[0,1,0]
	v_mov_b32_e32 v42, v45
	v_pk_fma_f32 v[38:39], v[78:79], v[44:45], v[38:39] op_sel_hi:[1,0,1]
	s_waitcnt lgkmcnt(0)
; #define LAS __attribute__((address_space(3)))
; DI void ssm_step_lds(const SsmC& c, const LAS bf16_t* up_, float& xr, float& xi) {
;     const LAS f32x4* up = (const LAS f32x4*)up_;
;     const f32x4 u0 = up[0], u1 = up[1], u2 = up[2], u3 = up[3];
;     float sr = 0.f, si = 0.f;
; #pragma unroll
;     for (int e = 0; e < 4; ++e) { sr += c.bbr[e] * u0[e]; si += c.bbi[e] * u0[e]; }
; #pragma unroll
;     for (int e = 0; e < 4; ++e) { sr += c.bbr[4 + e] * u1[e]; si += c.bbi[4 + e] * u1[e]; }
; #pragma unroll
;     for (int e = 0; e < 4; ++e) { sr += c.bbr[8 + e] * u2[e]; si += c.bbi[8 + e] * u2[e]; }
; #pragma unroll
;     for (int e = 0; e < 4; ++e) { sr += c.bbr[12 + e] * u3[e]; si += c.bbi[12 + e] * u3[e]; }
;     const float nxr = c.ar * xr - c.ai * xi + sr, nxi = c.ar * xi + c.ai * xr + si; xr = nxr; xi = nxi;
; }
; DI void ssm_s3(CArgs& a, int l, int it, int lane, LAS bf16_t* Xs  , LAS bf16_t* Us) {
;     ...
;     bf16x8 cf[4];
; #pragma unroll
;     for (int kk = 0; kk < 4; ++kk) { const int k = 32 * kk + 8 * fq; const bool im = k >= 64;
;         const float* src = (im ? a.in[I_CIM] : a.in[I_CRE]) + ((size_t)((l * 32 + g) * 16 + fr)) * 64 + (k & 63);
;         const f32x4 v0 = *(const f32x4*)src, v1 = *(const f32x4*)(src + 4); const float sg = im ? -1.f : 1.f;
;         u32x4 w; w.x = pk2(sg * v0[0], sg * v0[1]); w.y = pk2(sg * v0[2], sg * v0[3]); w.z = pk2(sg * v1[0], sg * v1[1]); w.w = pk2(sg * v1[2], sg * v1[3]);
;         cf[kk] = __builtin_bit_cast(bf16x8, w); }
;     const f32x4 dsk = *(const f32x4*)(a.in[I_SD] + l * 512 + g * 16 + 4 * fq);
;     const f32x2 x0 = ((const f32x2*)(a.ws + WS_XIN))[(size_t)it * 64 + lane];
;     float xr = x0.x, xi = x0.y;
;     bf16_t* gb = (bf16_t*)(a.ws + WS_G);
;     ssm_stage_u(up, Us, lane);
;     for (int sub = 0; sub < 4; ++sub) {
; #pragma unroll 4
;         for (int tt = 0; tt < 32; ++tt) { ssm_step_lds(c, Us + (32 * sub + tt) * 32, xr, xi);
;             Xs[tt * 136 + lane] = (bf16_t)f2bf(xr); Xs[tt * 136 + 64 + lane] = (bf16_t)f2bf(xi); }
;         asm volatile("s_waitcnt lgkmcnt(0)" ::: "memory");
; #pragma unroll
;         for (int m = 0; m < 2; ++m) {
;             float zz = 0.f; asm volatile("" : "+v"(zz)); f32x4 acc = {zz, zz, zz, zz};
; #pragma unroll
;             for (int kk = 0; kk < 4; ++kk) { const bf16x8 xf = lds_b128(Xs + (16 * m + fr) * 136 + 32 * kk + 8 * fq); acc = MFMA16(cf[kk], xf, acc); }
	v_mov_b32_e32 v44, v131
	v_pk_fma_f32 v[38:39], v[98:99], v[42:43], v[38:39] op_sel_hi:[1,0,1]
	v_pk_fma_f32 v[38:39], v[100:101], v[46:47], v[38:39] op_sel_hi:[1,0,1]
	s_nop 0
	v_pk_fma_f32 v[38:39], v[102:103], v[46:47], v[38:39] op_sel:[0,1,0]
	s_nop 0
	v_pk_fma_f32 v[38:39], v[104:105], v[48:49], v[38:39] op_sel_hi:[1,0,1]
	s_nop 0
	v_pk_fma_f32 v[38:39], v[106:107], v[48:49], v[38:39] op_sel:[0,1,0]
	v_pk_fma_f32 v[38:39], v[108:109], v[50:51], v[38:39] op_sel_hi:[1,0,1]
	s_nop 0
	v_pk_fma_f32 v[38:39], v[110:111], v[50:51], v[38:39] op_sel:[0,1,0]
	s_nop 0
	v_pk_fma_f32 v[38:39], v[112:113], v[52:53], v[38:39] op_sel_hi:[1,0,1]
	s_nop 0
	v_pk_fma_f32 v[38:39], v[114:115], v[52:53], v[38:39] op_sel:[0,1,0]
	v_pk_mul_f32 v[42:43], v[72:73], v[4:5]
	v_pk_fma_f32 v[38:39], v[116:117], v[128:129], v[38:39] op_sel_hi:[1,0,1]
	s_nop 0
	v_pk_fma_f32 v[38:39], v[118:119], v[128:129], v[38:39] op_sel:[0,1,0]
	s_nop 0
	v_pk_fma_f32 v[38:39], v[120:121], v[130:131], v[38:39] op_sel_hi:[1,0,1]
	s_nop 0
	v_pk_fma_f32 v[38:39], v[122:123], v[44:45], v[38:39] op_sel_hi:[1,0,1]
	v_pk_fma_f32 v[44:45], v[70:71], v[4:5], v[42:43] op_sel:[0,0,1] op_sel_hi:[1,1,0]
	v_pk_fma_f32 v[4:5], v[70:71], v[4:5], v[42:43] op_sel:[0,0,1] op_sel_hi:[1,1,0] neg_lo:[0,0,1] neg_hi:[0,0,1]
	s_nop 0
	v_mov_b32_e32 v45, v5
	v_pk_add_f32 v[4:5], v[44:45], v[38:39]
	s_nop 0
	v_bfe_u32 v38, v5, 16, 1
	v_add3_u32 v38, v5, v38, s33
	ds_write_b16_d16_hi v40, v38 offset:544
	v_bfe_u32 v38, v4, 16, 1
	v_add3_u32 v38, v4, v38, s33
	ds_write_b16_d16_hi v40, v38 offset:672
	v_mov_b32_e32 v38, s5
	ds_read_b128 v[42:45], v38
	s_add_i32 s5, s4, 0x118d0
	v_mov_b32_e32 v38, s5
	s_add_i32 s5, s4, 0x118e0
	ds_read_b128 v[46:49], v38
	v_mov_b32_e32 v38, s5
	s_add_i32 s4, s4, 0x118f0
	ds_read_b128 v[50:53], v38
	v_mov_b32_e32 v38, s4
	ds_read_b128 v[128:131], v38
	s_waitcnt lgkmcnt(3)
	v_pk_fma_f32 v[38:39], v[74:75], v[42:43], 0 op_sel_hi:[1,0,0]
	s_cmp_eq_u32 s3, 0
	v_pk_fma_f32 v[38:39], v[76:77], v[42:43], v[38:39] op_sel:[0,1,0]
	v_mov_b32_e32 v42, v45
	v_pk_fma_f32 v[38:39], v[78:79], v[44:45], v[38:39] op_sel_hi:[1,0,1]
	s_waitcnt lgkmcnt(0)
	v_mov_b32_e32 v44, v131
	v_pk_fma_f32 v[38:39], v[98:99], v[42:43], v[38:39] op_sel_hi:[1,0,1]
	v_pk_fma_f32 v[38:39], v[100:101], v[46:47], v[38:39] op_sel_hi:[1,0,1]
	s_nop 0
	v_pk_fma_f32 v[38:39], v[102:103], v[46:47], v[38:39] op_sel:[0,1,0]
	s_nop 0
	v_pk_fma_f32 v[38:39], v[104:105], v[48:49], v[38:39] op_sel_hi:[1,0,1]
	s_nop 0
	v_pk_fma_f32 v[38:39], v[106:107], v[48:49], v[38:39] op_sel:[0,1,0]
	v_pk_fma_f32 v[38:39], v[108:109], v[50:51], v[38:39] op_sel_hi:[1,0,1]
	s_nop 0
	v_pk_fma_f32 v[38:39], v[110:111], v[50:51], v[38:39] op_sel:[0,1,0]
	s_nop 0
	v_pk_fma_f32 v[38:39], v[112:113], v[52:53], v[38:39] op_sel_hi:[1,0,1]
	s_nop 0
	v_pk_fma_f32 v[38:39], v[114:115], v[52:53], v[38:39] op_sel:[0,1,0]
	v_pk_mul_f32 v[42:43], v[72:73], v[4:5]
	v_pk_fma_f32 v[38:39], v[116:117], v[128:129], v[38:39] op_sel_hi:[1,0,1]
	s_nop 0
	v_pk_fma_f32 v[38:39], v[118:119], v[128:129], v[38:39] op_sel:[0,1,0]
	s_nop 0
	v_pk_fma_f32 v[38:39], v[120:121], v[130:131], v[38:39] op_sel_hi:[1,0,1]
	s_nop 0
	v_pk_fma_f32 v[38:39], v[122:123], v[44:45], v[38:39] op_sel_hi:[1,0,1]
	v_pk_fma_f32 v[44:45], v[70:71], v[4:5], v[42:43] op_sel:[0,0,1] op_sel_hi:[1,1,0]
	v_pk_fma_f32 v[4:5], v[70:71], v[4:5], v[42:43] op_sel:[0,0,1] op_sel_hi:[1,1,0] neg_lo:[0,0,1] neg_hi:[0,0,1]
	s_nop 0
	v_mov_b32_e32 v45, v5
	v_pk_add_f32 v[38:39], v[44:45], v[38:39]
	s_nop 0
	v_bfe_u32 v4, v39, 16, 1
	v_add3_u32 v4, v39, v4, s33
	ds_write_b16_d16_hi v40, v4 offset:816
	v_bfe_u32 v4, v38, 16, 1
	v_add3_u32 v4, v38, v4, s33
	ds_write_b16_d16_hi v40, v4 offset:944
	v_add_u32_e32 v40, 0x440, v40
	s_cbranch_scc0 .LBB0_180
	v_xor_b32_e32 v19, 0x80000000, v19
	v_xor_b32_e32 v18, 0x80000000, v18
	v_cvt_pk_bf16_f32 v18, v18, v19
	v_xor_b32_e32 v19, 0x80000000, v20
	v_xor_b32_e32 v20, 0x80000000, v21
	v_cvt_pk_bf16_f32 v19, v19, v20
	v_mov_b32_e32 v20, v81
	v_cvt_pk_bf16_f32 v4, v34, v35
	v_cvt_pk_bf16_f32 v5, v36, v37
	v_cvt_pk_bf16_f32 v6, v6, v7
	v_cvt_pk_bf16_f32 v7, v8, v9
	v_cvt_pk_bf16_f32 v8, v30, v31
	v_cvt_pk_bf16_f32 v9, v32, v33
	v_xor_b32_e32 v15, 0x80000000, v15
	v_xor_b32_e32 v14, 0x80000000, v14
	s_waitcnt lgkmcnt(0)
	ds_read_b128 v[30:33], v126
	v_cvt_pk_bf16_f32 v14, v14, v15
	v_xor_b32_e32 v15, 0x80000000, v16
	v_xor_b32_e32 v16, 0x80000000, v17
	v_cvt_pk_bf16_f32 v15, v15, v16
	v_xor_b32_e32 v16, 0x80000000, v23
	v_xor_b32_e32 v17, 0x80000000, v22
	v_cvt_pk_bf16_f32 v16, v17, v16
	v_xor_b32_e32 v17, 0x80000000, v24
	v_xor_b32_e32 v22, 0x80000000, v25
	v_cvt_pk_bf16_f32 v17, v17, v22
	v_mov_b32_e32 v21, v20
	v_mov_b32_e32 v22, v20
	v_mov_b32_e32 v23, v20
	v_cvt_pk_bf16_f32 v10, v10, v11
	v_cvt_pk_bf16_f32 v11, v12, v13
	s_waitcnt lgkmcnt(0)
	v_mfma_f32_16x16x32_bf16 v[20:23], v[4:7], v[30:33], v[20:23]
	ds_read_b128 v[30:33], v126 offset:64
	v_xor_b32_e32 v12, 0x80000000, v27
	v_xor_b32_e32 v13, 0x80000000, v26
	v_cvt_pk_bf16_f32 v12, v13, v12
	v_xor_b32_e32 v13, 0x80000000, v28
	v_xor_b32_e32 v26, 0x80000000, v29
	v_cvt_pk_bf16_f32 v13, v13, v26
	s_waitcnt lgkmcnt(0)
	v_mfma_f32_16x16x32_bf16 v[20:23], v[8:11], v[30:33], v[20:23]
	ds_read_b128 v[30:33], v126 offset:128
	s_lshl_b32 s36, s1, 1
	s_lshl_b64 s[4:5], s[6:7], 7
	s_waitcnt lgkmcnt(0)
	v_mfma_f32_16x16x32_bf16 v[20:23], v[12:15], v[30:33], v[20:23]
	ds_read_b128 v[30:33], v126 offset:192
	v_lshl_add_u64 v[28:29], v[60:61], 0, s[36:37]
	v_or_b32_e32 v26, s4, v54
	s_waitcnt lgkmcnt(0)
; DI unsigned pk2(float lo, float hi) { f32x2 v = {lo, hi}; bf16x2_t b = __builtin_convertvector(v, bf16x2_t); return __builtin_bit_cast(unsigned, b); }
; DI float bflo(unsigned w) { return __uint_as_float(w << 16); }
; DI float bfhi(unsigned w) { return __uint_as_float(w & 0xffff0000u); }
; DI float geluf_(float x) { const float a = 0.7978845608028654f * (x + 0.044715f * x * x * x); const float t = 1.f - 2.f * __builtin_amdgcn_rcpf(__expf(2.f * a) + 1.f); return 0.5f * x * (1.f + t); }
; #define MFMA16(a, b, c) __builtin_amdgcn_mfma_f32_16x16x32_bf16((a), (b), (c), 0, 0, 0)
; DI void ssm_s3(CArgs& a, int l, int it, int lane, LAS bf16_t* Xs  , LAS bf16_t* Us) {
;     ...
;         for (int m = 0; m < 2; ++m) {
;             float zz = 0.f; asm volatile("" : "+v"(zz)); f32x4 acc = {zz, zz, zz, zz};
; #pragma unroll
;             for (int kk = 0; kk < 4; ++kk) { const bf16x8 xf = lds_b128(Xs + (16 * m + fr) * 136 + 32 * kk + 8 * fq); acc = MFMA16(cf[kk], xf, acc); }
;             const size_t tg = t0 + 32 * sub + 16 * m + fr;
;             const u32x2 uw = *(const u32x2*)(zb + tg * NZ + ZU + g * 16 + 4 * fq);
;             const float y0 = geluf_(acc[0] + dsk[0] * bflo(uw.x)), y1 = geluf_(acc[1] + dsk[1] * bfhi(uw.x)), y2 = geluf_(acc[2] + dsk[2] * bflo(uw.y)), y3 = geluf_(acc[3] + dsk[3] * bfhi(uw.y));
;             u32x2 ow; ow.x = pk2(y0, y1); ow.y = pk2(y2, y3);
;             *(u32x2*)(gb + tg * 512 + g * 16 + 4 * fq) = ow;
	v_mfma_f32_16x16x32_bf16 v[20:23], v[16:19], v[30:33], v[20:23]
	v_mad_u64_u32 v[30:31], s[6:7], v26, s55, v[28:29]
	v_mad_i32_i24 v31, s5, v220, v31
	global_load_dwordx2 v[32:33], v[30:31], off
	s_mov_b32 s98, 0x1a000
	s_mov_b32 s99, 0
	v_lshl_add_u64 v[248:249], v[30:31], 0, s[98:99]
	global_load_dwordx2 v[234:235], v[248:249], off
	v_lshl_add_u64 v[248:249], v[248:249], 0, s[98:99]
	global_load_dwordx2 v[236:237], v[248:249], off
	v_lshl_add_u64 v[248:249], v[248:249], 0, s[98:99]
	global_load_dwordx2 v[238:239], v[248:249], off
	v_lshl_add_u64 v[248:249], v[248:249], 0, s[98:99]
	global_load_dwordx2 v[240:241], v[248:249], off
	v_lshl_add_u64 v[248:249], v[248:249], 0, s[98:99]
	global_load_dwordx2 v[242:243], v[248:249], off
	v_lshl_add_u64 v[248:249], v[248:249], 0, s[98:99]
	global_load_dwordx2 v[244:245], v[248:249], off
	v_lshl_add_u64 v[248:249], v[248:249], 0, s[98:99]
	global_load_dwordx2 v[246:247], v[248:249], off
	v_mov_b32_e32 v27, s5
	v_lshl_add_u64 v[24:25], v[62:63], 0, s[36:37]
	s_movk_i32 s1, 0xf800
	s_waitcnt vmcnt(7)
	v_lshlrev_b32_e32 v34, 16, v32
	v_and_b32_e32 v35, 0xffff0000, v32
	v_pk_fma_f32 v[20:21], v[0:1], v[34:35], v[20:21]
	s_nop 0
	v_mul_f32_e32 v32, 0x3d372713, v20
	v_mul_f32_e32 v32, v20, v32
	v_fma_f32 v32, v20, v32, v20
	v_mul_f32_e32 v32, 0x3f4c422a, v32
	v_add_f32_e32 v32, v32, v32
	v_mul_f32_e32 v32, 0x3fb8aa3b, v32
	v_exp_f32_e32 v32, v32
	s_nop 0
	v_add_f32_e32 v32, 1.0, v32
	v_rcp_f32_e32 v34, v32
	v_mul_f32_e32 v32, 0x3d372713, v21
	v_mul_f32_e32 v32, v21, v32
	v_fma_f32 v32, v21, v32, v21
	v_mul_f32_e32 v32, 0x3f4c422a, v32
	v_add_f32_e32 v32, v32, v32
	v_mul_f32_e32 v32, 0x3fb8aa3b, v32
	v_exp_f32_e32 v32, v32
	v_pk_mul_f32 v[20:21], v[20:21], 0.5 op_sel_hi:[1,0]
	v_add_f32_e32 v32, 1.0, v32
	v_rcp_f32_e32 v35, v32
	v_lshlrev_b32_e32 v32, 16, v33
	v_and_b32_e32 v33, 0xffff0000, v33
	v_pk_fma_f32 v[22:23], v[2:3], v[32:33], v[22:23]
	v_pk_fma_f32 v[34:35], v[34:35], 2.0, 1.0 op_sel_hi:[1,0,0] neg_lo:[1,0,0] neg_hi:[1,0,0]
	v_mul_f32_e32 v32, 0x3d372713, v22
	v_mul_f32_e32 v33, 0x3d372713, v23
	v_mul_f32_e32 v32, v22, v32
	v_mul_f32_e32 v33, v23, v33
	v_fma_f32 v32, v22, v32, v22
	v_fma_f32 v33, v23, v33, v23
	v_mul_f32_e32 v32, 0x3f4c422a, v32
	v_mul_f32_e32 v33, 0x3f4c422a, v33
	v_add_f32_e32 v32, v32, v32
	v_add_f32_e32 v33, v33, v33
	v_mul_f32_e32 v32, 0x3fb8aa3b, v32
	v_mul_f32_e32 v33, 0x3fb8aa3b, v33
	v_exp_f32_e32 v32, v32
	v_exp_f32_e32 v33, v33
	v_pk_add_f32 v[34:35], v[34:35], 1.0 op_sel_hi:[1,0]
	v_pk_mul_f32 v[22:23], v[22:23], 0.5 op_sel_hi:[1,0]
	v_add_f32_e32 v32, 1.0, v32
	v_add_f32_e32 v33, 1.0, v33
	v_rcp_f32_e32 v32, v32
	v_rcp_f32_e32 v33, v33
	v_pk_mul_f32 v[20:21], v[20:21], v[34:35]
	v_pk_fma_f32 v[32:33], v[32:33], 2.0, 1.0 op_sel_hi:[1,0,0] neg_lo:[1,0,0] neg_hi:[1,0,0]
	s_nop 0
	v_pk_add_f32 v[32:33], v[32:33], 1.0 op_sel_hi:[1,0]
	s_nop 0
	v_pk_mul_f32 v[22:23], v[22:23], v[32:33]
	v_cvt_pk_bf16_f32 v32, v20, v21
	v_lshlrev_b64 v[20:21], 10, v[26:27]
	v_cvt_pk_bf16_f32 v33, v22, v23
	v_lshl_add_u64 v[22:23], v[24:25], 0, v[20:21]
	global_store_dwordx2 v[22:23], v[32:33], off
	v_add_co_u32_e32 v22, vcc, s79, v30
	v_mov_b32_e32 v32, v81
	s_nop 0
	v_addc_co_u32_e32 v23, vcc, 0, v31, vcc
	ds_read_b128 v[40:43], v126 offset:4352
	v_mov_b32_e32 v33, v32
	v_mov_b32_e32 v34, v32
	v_mov_b32_e32 v35, v32
	s_waitcnt vmcnt(6)
	v_mov_b32_e32 v22, v234
	v_mov_b32_e32 v23, v235
	v_lshlrev_b32_e32 v30, 16, v22
	s_waitcnt lgkmcnt(0)
	v_mfma_f32_16x16x32_bf16 v[32:35], v[4:7], v[40:43], v[32:35]
	ds_read_b128 v[40:43], v126 offset:4416
	v_and_b32_e32 v31, 0xffff0000, v22
	s_waitcnt lgkmcnt(0)
	v_mfma_f32_16x16x32_bf16 v[32:35], v[8:11], v[40:43], v[32:35]
	ds_read_b128 v[40:43], v126 offset:4480
	s_waitcnt lgkmcnt(0)
	v_mfma_f32_16x16x32_bf16 v[32:35], v[12:15], v[40:43], v[32:35]
	ds_read_b128 v[40:43], v126 offset:4544
	s_waitcnt lgkmcnt(0)
	v_mfma_f32_16x16x32_bf16 v[32:35], v[16:19], v[40:43], v[32:35]
	s_nop 7
	v_pk_fma_f32 v[30:31], v[0:1], v[30:31], v[32:33]
	s_nop 0
	v_mul_f32_e32 v22, 0x3d372713, v30
	v_mul_f32_e32 v22, v30, v22
	v_fma_f32 v22, v30, v22, v30
	v_mul_f32_e32 v22, 0x3f4c422a, v22
	v_add_f32_e32 v22, v22, v22
	v_mul_f32_e32 v22, 0x3fb8aa3b, v22
	v_exp_f32_e32 v22, v22
	s_nop 0
	v_add_f32_e32 v22, 1.0, v22
	v_rcp_f32_e32 v32, v22
	v_mul_f32_e32 v22, 0x3d372713, v31
	v_mul_f32_e32 v22, v31, v22
	v_fma_f32 v22, v31, v22, v31
	v_mul_f32_e32 v22, 0x3f4c422a, v22
	v_add_f32_e32 v22, v22, v22
	v_mul_f32_e32 v22, 0x3fb8aa3b, v22
	v_exp_f32_e32 v22, v22
	v_pk_mul_f32 v[30:31], v[30:31], 0.5 op_sel_hi:[1,0]
	v_add_f32_e32 v22, 1.0, v22
	v_rcp_f32_e32 v33, v22
	v_lshlrev_b32_e32 v22, 16, v23
	v_and_b32_e32 v23, 0xffff0000, v23
	v_pk_fma_f32 v[22:23], v[2:3], v[22:23], v[34:35]
	v_pk_fma_f32 v[32:33], v[32:33], 2.0, 1.0 op_sel_hi:[1,0,0] neg_lo:[1,0,0] neg_hi:[1,0,0]
	s_nop 0
	v_pk_add_f32 v[32:33], v[32:33], 1.0 op_sel_hi:[1,0]
	s_nop 0
	v_pk_mul_f32 v[30:31], v[30:31], v[32:33]
	v_mul_f32_e32 v32, 0x3d372713, v22
	v_mul_f32_e32 v33, 0x3d372713, v23
	v_mul_f32_e32 v32, v22, v32
	v_mul_f32_e32 v33, v23, v33
	v_fma_f32 v32, v22, v32, v22
	v_fma_f32 v33, v23, v33, v23
	v_mul_f32_e32 v32, 0x3f4c422a, v32
	v_mul_f32_e32 v33, 0x3f4c422a, v33
	v_add_f32_e32 v32, v32, v32
	v_add_f32_e32 v33, v33, v33
	v_mul_f32_e32 v32, 0x3fb8aa3b, v32
	v_mul_f32_e32 v33, 0x3fb8aa3b, v33
	v_exp_f32_e32 v32, v32
	v_exp_f32_e32 v33, v33
	v_pk_mul_f32 v[22:23], v[22:23], 0.5 op_sel_hi:[1,0]
	v_add_f32_e32 v32, 1.0, v32
	v_add_f32_e32 v33, 1.0, v33
	v_rcp_f32_e32 v32, v32
	v_rcp_f32_e32 v33, v33
	s_nop 0
	v_pk_fma_f32 v[32:33], v[32:33], 2.0, 1.0 op_sel_hi:[1,0,0] neg_lo:[1,0,0] neg_hi:[1,0,0]
	s_nop 0
	v_pk_add_f32 v[32:33], v[32:33], 1.0 op_sel_hi:[1,0]
	s_nop 0
	v_pk_mul_f32 v[32:33], v[22:23], v[32:33]
	v_cvt_pk_bf16_f32 v22, v30, v31
	v_or_b32_e32 v30, 0x4000, v20
	v_mov_b32_e32 v31, v21
	v_cvt_pk_bf16_f32 v23, v32, v33
	v_lshl_add_u64 v[30:31], v[24:25], 0, v[30:31]
	global_store_dwordx2 v[30:31], v[22:23], off
	s_waitcnt lgkmcnt(0)
	v_mov_b32_e32 v22, v124
; #define LAS __attribute__((address_space(3)))
; DI unsigned f2bf(float f) { unsigned u = __builtin_bit_cast(unsigned, f); return (u + 0x7fffu + ((u >> 16) & 1u)) >> 16; }
; DI void ssm_step_lds(const SsmC& c, const LAS bf16_t* up_, float& xr, float& xi) {
;     const LAS f32x4* up = (const LAS f32x4*)up_;
;     const f32x4 u0 = up[0], u1 = up[1], u2 = up[2], u3 = up[3];
;     float sr = 0.f, si = 0.f;
; #pragma unroll
;     for (int e = 0; e < 4; ++e) { sr += c.bbr[e] * u0[e]; si += c.bbi[e] * u0[e]; }
; #pragma unroll
;     for (int e = 0; e < 4; ++e) { sr += c.bbr[4 + e] * u1[e]; si += c.bbi[4 + e] * u1[e]; }
; #pragma unroll
;     for (int e = 0; e < 4; ++e) { sr += c.bbr[8 + e] * u2[e]; si += c.bbi[8 + e] * u2[e]; }
; #pragma unroll
;     for (int e = 0; e < 4; ++e) { sr += c.bbr[12 + e] * u3[e]; si += c.bbi[12 + e] * u3[e]; }
;     const float nxr = c.ar * xr - c.ai * xi + sr, nxi = c.ar * xi + c.ai * xr + si; xr = nxr; xi = nxi;
; }
; DI void ssm_s3(CArgs& a, int l, int it, int lane, LAS bf16_t* Xs  , LAS bf16_t* Us) {
;     ...
;     for (int sub = 0; sub < 4; ++sub) {
; #pragma unroll 4
;         for (int tt = 0; tt < 32; ++tt) { ssm_step_lds(c, Us + (32 * sub + tt) * 32, xr, xi);
;             Xs[tt * 136 + lane] = (bf16_t)f2bf(xr); Xs[tt * 136 + 64 + lane] = (bf16_t)f2bf(xi); }
.LBB0_182:
	s_add_i32 s3, s0, s1
	s_add_i32 s4, s3, 0x12000
	v_mov_b32_e32 v23, s4
	ds_read_b128 v[30:33], v23
	s_add_i32 s4, s3, 0x12010
	v_mov_b32_e32 v23, s4
	ds_read_b128 v[34:37], v23
	s_add_i32 s4, s3, 0x12020
	s_waitcnt lgkmcnt(1)
	v_pk_fma_f32 v[48:49], v[74:75], v[30:31], 0 op_sel_hi:[1,0,0]
	v_mov_b32_e32 v23, s4
	v_pk_fma_f32 v[30:31], v[76:77], v[30:31], v[48:49] op_sel:[0,1,0]
	ds_read_b128 v[40:43], v23
	v_pk_fma_f32 v[30:31], v[78:79], v[32:33], v[30:31] op_sel_hi:[1,0,1]
	v_pk_fma_f32 v[30:31], v[98:99], v[32:33], v[30:31] op_sel:[0,1,0]
	s_add_i32 s4, s3, 0x12030
	s_waitcnt lgkmcnt(1)
	v_pk_fma_f32 v[30:31], v[100:101], v[34:35], v[30:31] op_sel_hi:[1,0,1]
	v_mov_b32_e32 v23, s4
	v_pk_fma_f32 v[30:31], v[102:103], v[34:35], v[30:31] op_sel:[0,1,0]
	v_pk_fma_f32 v[30:31], v[104:105], v[36:37], v[30:31] op_sel_hi:[1,0,1]
	ds_read_b128 v[44:47], v23
	v_pk_fma_f32 v[30:31], v[106:107], v[36:37], v[30:31] op_sel:[0,1,0]
	s_waitcnt lgkmcnt(1)
	v_pk_fma_f32 v[30:31], v[108:109], v[40:41], v[30:31] op_sel_hi:[1,0,1]
	v_pk_mul_f32 v[32:33], v[72:73], v[38:39]
	v_pk_fma_f32 v[30:31], v[110:111], v[40:41], v[30:31] op_sel:[0,1,0]
	s_add_i32 s4, s3, 0x12040
	v_pk_fma_f32 v[30:31], v[112:113], v[42:43], v[30:31] op_sel_hi:[1,0,1]
	s_addk_i32 s1, 0x100
	v_pk_fma_f32 v[30:31], v[114:115], v[42:43], v[30:31] op_sel:[0,1,0]
	s_waitcnt lgkmcnt(0)
	v_pk_fma_f32 v[30:31], v[116:117], v[44:45], v[30:31] op_sel_hi:[1,0,1]
	s_nop 0
	v_pk_fma_f32 v[30:31], v[118:119], v[44:45], v[30:31] op_sel:[0,1,0]
	s_nop 0
	v_pk_fma_f32 v[30:31], v[120:121], v[46:47], v[30:31] op_sel_hi:[1,0,1]
	s_nop 0
	v_pk_fma_f32 v[30:31], v[122:123], v[46:47], v[30:31] op_sel:[0,1,0]
	v_pk_fma_f32 v[34:35], v[70:71], v[38:39], v[32:33] op_sel:[0,0,1] op_sel_hi:[1,1,0]
	v_pk_fma_f32 v[32:33], v[70:71], v[38:39], v[32:33] op_sel:[0,0,1] op_sel_hi:[1,1,0] neg_lo:[0,0,1] neg_hi:[0,0,1]
	s_nop 0
	v_mov_b32_e32 v35, v33
	v_pk_add_f32 v[46:47], v[34:35], v[30:31]
	s_nop 0
	v_bfe_u32 v23, v47, 16, 1
	v_add3_u32 v23, v47, v23, s33
	ds_write_b16_d16_hi v22, v23
	v_bfe_u32 v23, v46, 16, 1
	v_add3_u32 v23, v46, v23, s33
	ds_write_b16_d16_hi v22, v23 offset:128
	v_mov_b32_e32 v23, s4
	ds_read_b128 v[30:33], v23
	s_add_i32 s4, s3, 0x12050
	v_mov_b32_e32 v23, s4
	ds_read_b128 v[34:37], v23
	s_add_i32 s4, s3, 0x12060
	s_waitcnt lgkmcnt(1)
	v_pk_fma_f32 v[48:49], v[74:75], v[30:31], 0 op_sel_hi:[1,0,0]
	v_mov_b32_e32 v23, s4
	v_pk_fma_f32 v[30:31], v[76:77], v[30:31], v[48:49] op_sel:[0,1,0]
	ds_read_b128 v[38:41], v23
	v_pk_fma_f32 v[30:31], v[78:79], v[32:33], v[30:31] op_sel_hi:[1,0,1]
	v_pk_fma_f32 v[30:31], v[98:99], v[32:33], v[30:31] op_sel:[0,1,0]
	s_add_i32 s4, s3, 0x12070
	s_waitcnt lgkmcnt(1)
	v_pk_fma_f32 v[30:31], v[100:101], v[34:35], v[30:31] op_sel_hi:[1,0,1]
	v_mov_b32_e32 v23, s4
	v_pk_fma_f32 v[30:31], v[102:103], v[34:35], v[30:31] op_sel:[0,1,0]
	v_pk_fma_f32 v[30:31], v[104:105], v[36:37], v[30:31] op_sel_hi:[1,0,1]
	ds_read_b128 v[42:45], v23
	v_pk_fma_f32 v[30:31], v[106:107], v[36:37], v[30:31] op_sel:[0,1,0]
	s_waitcnt lgkmcnt(1)
	v_pk_fma_f32 v[30:31], v[108:109], v[38:39], v[30:31] op_sel_hi:[1,0,1]
	v_pk_mul_f32 v[32:33], v[72:73], v[46:47]
	v_pk_fma_f32 v[30:31], v[110:111], v[38:39], v[30:31] op_sel:[0,1,0]
	s_add_i32 s4, s3, 0x12080
	v_pk_fma_f32 v[30:31], v[112:113], v[40:41], v[30:31] op_sel_hi:[1,0,1]
	s_nop 0
	v_pk_fma_f32 v[30:31], v[114:115], v[40:41], v[30:31] op_sel:[0,1,0]
	s_waitcnt lgkmcnt(0)
	v_pk_fma_f32 v[30:31], v[116:117], v[42:43], v[30:31] op_sel_hi:[1,0,1]
	s_nop 0
	v_pk_fma_f32 v[30:31], v[118:119], v[42:43], v[30:31] op_sel:[0,1,0]
	s_nop 0
	v_pk_fma_f32 v[30:31], v[120:121], v[44:45], v[30:31] op_sel_hi:[1,0,1]
	s_nop 0
	v_pk_fma_f32 v[30:31], v[122:123], v[44:45], v[30:31] op_sel:[0,1,0]
	v_pk_fma_f32 v[34:35], v[70:71], v[46:47], v[32:33] op_sel:[0,0,1] op_sel_hi:[1,1,0]
	v_pk_fma_f32 v[32:33], v[70:71], v[46:47], v[32:33] op_sel:[0,0,1] op_sel_hi:[1,1,0] neg_lo:[0,0,1] neg_hi:[0,0,1]
	s_nop 0
	v_mov_b32_e32 v35, v33
	v_pk_add_f32 v[46:47], v[34:35], v[30:31]
	s_nop 0
	v_bfe_u32 v23, v47, 16, 1
	v_add3_u32 v23, v47, v23, s33
	ds_write_b16_d16_hi v22, v23 offset:272
	v_bfe_u32 v23, v46, 16, 1
	v_add3_u32 v23, v46, v23, s33
	ds_write_b16_d16_hi v22, v23 offset:400
	v_mov_b32_e32 v23, s4
	ds_read_b128 v[30:33], v23
	s_add_i32 s4, s3, 0x12090
	v_mov_b32_e32 v23, s4
	ds_read_b128 v[34:37], v23
	s_add_i32 s4, s3, 0x120a0
	s_waitcnt lgkmcnt(1)
	v_pk_fma_f32 v[48:49], v[74:75], v[30:31], 0 op_sel_hi:[1,0,0]
	v_mov_b32_e32 v23, s4
	v_pk_fma_f32 v[30:31], v[76:77], v[30:31], v[48:49] op_sel:[0,1,0]
	ds_read_b128 v[38:41], v23
	v_pk_fma_f32 v[30:31], v[78:79], v[32:33], v[30:31] op_sel_hi:[1,0,1]
	v_pk_fma_f32 v[30:31], v[98:99], v[32:33], v[30:31] op_sel:[0,1,0]
	s_add_i32 s4, s3, 0x120b0
	s_waitcnt lgkmcnt(1)
	v_pk_fma_f32 v[30:31], v[100:101], v[34:35], v[30:31] op_sel_hi:[1,0,1]
	v_mov_b32_e32 v23, s4
	v_pk_fma_f32 v[30:31], v[102:103], v[34:35], v[30:31] op_sel:[0,1,0]
	v_pk_fma_f32 v[30:31], v[104:105], v[36:37], v[30:31] op_sel_hi:[1,0,1]
	ds_read_b128 v[42:45], v23
	v_pk_fma_f32 v[30:31], v[106:107], v[36:37], v[30:31] op_sel:[0,1,0]
	s_waitcnt lgkmcnt(1)
	v_pk_fma_f32 v[30:31], v[108:109], v[38:39], v[30:31] op_sel_hi:[1,0,1]
	v_pk_mul_f32 v[32:33], v[72:73], v[46:47]
	v_pk_fma_f32 v[30:31], v[110:111], v[38:39], v[30:31] op_sel:[0,1,0]
	s_add_i32 s4, s3, 0x120c0
	v_pk_fma_f32 v[30:31], v[112:113], v[40:41], v[30:31] op_sel_hi:[1,0,1]
	s_nop 0
	v_pk_fma_f32 v[30:31], v[114:115], v[40:41], v[30:31] op_sel:[0,1,0]
	s_waitcnt lgkmcnt(0)
; #define LAS __attribute__((address_space(3)))
; DI unsigned pk2(float lo, float hi) { f32x2 v = {lo, hi}; bf16x2_t b = __builtin_convertvector(v, bf16x2_t); return __builtin_bit_cast(unsigned, b); }
; DI float bflo(unsigned w) { return __uint_as_float(w << 16); }
; DI float bfhi(unsigned w) { return __uint_as_float(w & 0xffff0000u); }
; DI float geluf_(float x) { const float a = 0.7978845608028654f * (x + 0.044715f * x * x * x); const float t = 1.f - 2.f * __builtin_amdgcn_rcpf(__expf(2.f * a) + 1.f); return 0.5f * x * (1.f + t); }
; #define MFMA16(a, b, c) __builtin_amdgcn_mfma_f32_16x16x32_bf16((a), (b), (c), 0, 0, 0)
; DI void ssm_step_lds(const SsmC& c, const LAS bf16_t* up_, float& xr, float& xi) {
;     const LAS f32x4* up = (const LAS f32x4*)up_;
;     const f32x4 u0 = up[0], u1 = up[1], u2 = up[2], u3 = up[3];
;     float sr = 0.f, si = 0.f;
; #pragma unroll
;     for (int e = 0; e < 4; ++e) { sr += c.bbr[e] * u0[e]; si += c.bbi[e] * u0[e]; }
; #pragma unroll
;     for (int e = 0; e < 4; ++e) { sr += c.bbr[4 + e] * u1[e]; si += c.bbi[4 + e] * u1[e]; }
; #pragma unroll
;     for (int e = 0; e < 4; ++e) { sr += c.bbr[8 + e] * u2[e]; si += c.bbi[8 + e] * u2[e]; }
; #pragma unroll
;     for (int e = 0; e < 4; ++e) { sr += c.bbr[12 + e] * u3[e]; si += c.bbi[12 + e] * u3[e]; }
;     const float nxr = c.ar * xr - c.ai * xi + sr, nxi = c.ar * xi + c.ai * xr + si; xr = nxr; xi = nxi;
; }
; DI void ssm_s3(CArgs& a, int l, int it, int lane, LAS bf16_t* Xs  , LAS bf16_t* Us) {
;     ...
;         for (int m = 0; m < 2; ++m) {
;             float zz = 0.f; asm volatile("" : "+v"(zz)); f32x4 acc = {zz, zz, zz, zz};
; #pragma unroll
;             for (int kk = 0; kk < 4; ++kk) { const bf16x8 xf = lds_b128(Xs + (16 * m + fr) * 136 + 32 * kk + 8 * fq); acc = MFMA16(cf[kk], xf, acc); }
;             const size_t tg = t0 + 32 * sub + 16 * m + fr;
;             const u32x2 uw = *(const u32x2*)(zb + tg * NZ + ZU + g * 16 + 4 * fq);
;             const float y0 = geluf_(acc[0] + dsk[0] * bflo(uw.x)), y1 = geluf_(acc[1] + dsk[1] * bfhi(uw.x)), y2 = geluf_(acc[2] + dsk[2] * bflo(uw.y)), y3 = geluf_(acc[3] + dsk[3] * bfhi(uw.y));
;             u32x2 ow; ow.x = pk2(y0, y1); ow.y = pk2(y2, y3);
;             *(u32x2*)(gb + tg * 512 + g * 16 + 4 * fq) = ow;
	v_pk_fma_f32 v[30:31], v[116:117], v[42:43], v[30:31] op_sel_hi:[1,0,1]
	s_nop 0
	v_pk_fma_f32 v[30:31], v[118:119], v[42:43], v[30:31] op_sel:[0,1,0]
	s_nop 0
	v_pk_fma_f32 v[30:31], v[120:121], v[44:45], v[30:31] op_sel_hi:[1,0,1]
	s_nop 0
	v_pk_fma_f32 v[30:31], v[122:123], v[44:45], v[30:31] op_sel:[0,1,0]
	v_pk_fma_f32 v[34:35], v[70:71], v[46:47], v[32:33] op_sel:[0,0,1] op_sel_hi:[1,1,0]
	v_pk_fma_f32 v[32:33], v[70:71], v[46:47], v[32:33] op_sel:[0,0,1] op_sel_hi:[1,1,0] neg_lo:[0,0,1] neg_hi:[0,0,1]
	s_nop 0
	v_mov_b32_e32 v35, v33
	v_pk_add_f32 v[46:47], v[34:35], v[30:31]
	s_nop 0
	v_bfe_u32 v23, v47, 16, 1
	v_add3_u32 v23, v47, v23, s33
	ds_write_b16_d16_hi v22, v23 offset:544
	v_bfe_u32 v23, v46, 16, 1
	v_add3_u32 v23, v46, v23, s33
	ds_write_b16_d16_hi v22, v23 offset:672
	v_mov_b32_e32 v23, s4
	ds_read_b128 v[30:33], v23
	s_add_i32 s4, s3, 0x120d0
	v_mov_b32_e32 v23, s4
	ds_read_b128 v[34:37], v23
	s_add_i32 s4, s3, 0x120e0
	s_waitcnt lgkmcnt(1)
	v_pk_fma_f32 v[48:49], v[74:75], v[30:31], 0 op_sel_hi:[1,0,0]
	v_mov_b32_e32 v23, s4
	v_pk_fma_f32 v[30:31], v[76:77], v[30:31], v[48:49] op_sel:[0,1,0]
	ds_read_b128 v[38:41], v23
	v_pk_fma_f32 v[30:31], v[78:79], v[32:33], v[30:31] op_sel_hi:[1,0,1]
	v_pk_fma_f32 v[30:31], v[98:99], v[32:33], v[30:31] op_sel:[0,1,0]
	s_add_i32 s3, s3, 0x120f0
	s_waitcnt lgkmcnt(1)
	v_pk_fma_f32 v[30:31], v[100:101], v[34:35], v[30:31] op_sel_hi:[1,0,1]
	v_mov_b32_e32 v23, s3
	v_pk_fma_f32 v[30:31], v[102:103], v[34:35], v[30:31] op_sel:[0,1,0]
	v_pk_fma_f32 v[30:31], v[104:105], v[36:37], v[30:31] op_sel_hi:[1,0,1]
	ds_read_b128 v[42:45], v23
	v_pk_fma_f32 v[30:31], v[106:107], v[36:37], v[30:31] op_sel:[0,1,0]
	s_waitcnt lgkmcnt(1)
	v_pk_fma_f32 v[30:31], v[108:109], v[38:39], v[30:31] op_sel_hi:[1,0,1]
	v_pk_mul_f32 v[32:33], v[72:73], v[46:47]
	v_pk_fma_f32 v[30:31], v[110:111], v[38:39], v[30:31] op_sel:[0,1,0]
	s_cmp_lg_u32 s1, 0
	v_pk_fma_f32 v[30:31], v[112:113], v[40:41], v[30:31] op_sel_hi:[1,0,1]
	s_nop 0
	v_pk_fma_f32 v[30:31], v[114:115], v[40:41], v[30:31] op_sel:[0,1,0]
	s_waitcnt lgkmcnt(0)
	v_pk_fma_f32 v[30:31], v[116:117], v[42:43], v[30:31] op_sel_hi:[1,0,1]
	s_nop 0
	v_pk_fma_f32 v[30:31], v[118:119], v[42:43], v[30:31] op_sel:[0,1,0]
	s_nop 0
	v_pk_fma_f32 v[30:31], v[120:121], v[44:45], v[30:31] op_sel_hi:[1,0,1]
	s_nop 0
	v_pk_fma_f32 v[30:31], v[122:123], v[44:45], v[30:31] op_sel:[0,1,0]
	v_pk_fma_f32 v[34:35], v[70:71], v[46:47], v[32:33] op_sel:[0,0,1] op_sel_hi:[1,1,0]
	v_pk_fma_f32 v[32:33], v[70:71], v[46:47], v[32:33] op_sel:[0,0,1] op_sel_hi:[1,1,0] neg_lo:[0,0,1] neg_hi:[0,0,1]
	s_nop 0
	v_mov_b32_e32 v35, v33
	v_pk_add_f32 v[38:39], v[34:35], v[30:31]
	s_nop 0
	v_bfe_u32 v23, v39, 16, 1
	v_add3_u32 v23, v39, v23, s33
	ds_write_b16_d16_hi v22, v23 offset:816
	v_bfe_u32 v23, v38, 16, 1
	v_add3_u32 v23, v38, v23, s33
	ds_write_b16_d16_hi v22, v23 offset:944
	v_add_u32_e32 v22, 0x440, v22
	s_cbranch_scc1 .LBB0_182
	v_mov_b32_e32 v30, v81
	s_waitcnt lgkmcnt(0)
	ds_read_b128 v[34:37], v126
	v_mov_b32_e32 v31, v30
	v_mov_b32_e32 v32, v30
	v_mov_b32_e32 v33, v30
	v_or_b32_e32 v40, 32, v26
	v_mad_u64_u32 v[22:23], s[4:5], v40, s55, v[28:29]
	s_waitcnt lgkmcnt(0)
	v_mfma_f32_16x16x32_bf16 v[30:33], v[4:7], v[34:37], v[30:33]
	ds_read_b128 v[34:37], v126 offset:64
	v_mad_i32_i24 v23, v27, s55, v23
	v_mov_b32_e32 v41, v27
	s_waitcnt lgkmcnt(0)
	v_mfma_f32_16x16x32_bf16 v[30:33], v[8:11], v[34:37], v[30:33]
	ds_read_b128 v[34:37], v126 offset:128
	s_movk_i32 s1, 0xf800
	s_waitcnt lgkmcnt(0)
	v_mfma_f32_16x16x32_bf16 v[30:33], v[12:15], v[34:37], v[30:33]
	ds_read_b128 v[34:37], v126 offset:192
	s_waitcnt lgkmcnt(0)
	v_mfma_f32_16x16x32_bf16 v[30:33], v[16:19], v[34:37], v[30:33]
	v_add_co_u32_e32 v22, vcc, s79, v22
	s_waitcnt vmcnt(5)
	v_mov_b32_e32 v34, v236
	v_mov_b32_e32 v35, v237
	v_lshlrev_b32_e32 v36, 16, v34
	v_and_b32_e32 v37, 0xffff0000, v34
	s_nop 2
	v_pk_fma_f32 v[30:31], v[0:1], v[36:37], v[30:31]
	v_addc_co_u32_e32 v23, vcc, 0, v23, vcc
	v_mul_f32_e32 v34, 0x3d372713, v30
	v_mul_f32_e32 v34, v30, v34
	v_fma_f32 v34, v30, v34, v30
	v_mul_f32_e32 v34, 0x3f4c422a, v34
	v_add_f32_e32 v34, v34, v34
	v_mul_f32_e32 v34, 0x3fb8aa3b, v34
	v_exp_f32_e32 v34, v34
	s_nop 0
	v_add_f32_e32 v34, 1.0, v34
	v_rcp_f32_e32 v36, v34
	v_mul_f32_e32 v34, 0x3d372713, v31
	v_mul_f32_e32 v34, v31, v34
	v_fma_f32 v34, v31, v34, v31
	v_mul_f32_e32 v34, 0x3f4c422a, v34
	v_add_f32_e32 v34, v34, v34
	v_mul_f32_e32 v34, 0x3fb8aa3b, v34
	v_exp_f32_e32 v34, v34
	v_pk_mul_f32 v[30:31], v[30:31], 0.5 op_sel_hi:[1,0]
	v_add_f32_e32 v34, 1.0, v34
	v_rcp_f32_e32 v37, v34
	v_lshlrev_b32_e32 v34, 16, v35
	v_and_b32_e32 v35, 0xffff0000, v35
	v_pk_fma_f32 v[32:33], v[2:3], v[34:35], v[32:33]
	v_pk_fma_f32 v[36:37], v[36:37], 2.0, 1.0 op_sel_hi:[1,0,0] neg_lo:[1,0,0] neg_hi:[1,0,0]
	v_mul_f32_e32 v34, 0x3d372713, v32
	v_mul_f32_e32 v35, 0x3d372713, v33
	v_mul_f32_e32 v34, v32, v34
	v_mul_f32_e32 v35, v33, v35
	v_fma_f32 v34, v32, v34, v32
	v_fma_f32 v35, v33, v35, v33
	v_mul_f32_e32 v34, 0x3f4c422a, v34
	v_mul_f32_e32 v35, 0x3f4c422a, v35
	v_add_f32_e32 v34, v34, v34
	v_add_f32_e32 v35, v35, v35
	v_mul_f32_e32 v34, 0x3fb8aa3b, v34
	v_mul_f32_e32 v35, 0x3fb8aa3b, v35
	v_exp_f32_e32 v34, v34
	v_exp_f32_e32 v35, v35
	v_pk_add_f32 v[36:37], v[36:37], 1.0 op_sel_hi:[1,0]
	v_pk_mul_f32 v[32:33], v[32:33], 0.5 op_sel_hi:[1,0]
	v_add_f32_e32 v34, 1.0, v34
	v_add_f32_e32 v35, 1.0, v35
	v_rcp_f32_e32 v34, v34
	v_rcp_f32_e32 v35, v35
	v_pk_mul_f32 v[30:31], v[30:31], v[36:37]
	v_pk_fma_f32 v[34:35], v[34:35], 2.0, 1.0 op_sel_hi:[1,0,0] neg_lo:[1,0,0] neg_hi:[1,0,0]
	s_nop 0
	v_pk_add_f32 v[34:35], v[34:35], 1.0 op_sel_hi:[1,0]
	v_cvt_pk_bf16_f32 v30, v30, v31
	v_pk_mul_f32 v[32:33], v[32:33], v[34:35]
	s_nop 0
	v_cvt_pk_bf16_f32 v31, v32, v33
	v_lshlrev_b64 v[32:33], 10, v[40:41]
	v_lshl_add_u64 v[32:33], v[24:25], 0, v[32:33]
	global_store_dwordx2 v[32:33], v[30:31], off
	v_mov_b32_e32 v30, v81
	ds_read_b128 v[34:37], v126 offset:4352
	v_mov_b32_e32 v31, v30
	v_mov_b32_e32 v32, v30
	v_mov_b32_e32 v33, v30
	s_waitcnt lgkmcnt(0)
; #define LAS __attribute__((address_space(3)))
; DI unsigned pk2(float lo, float hi) { f32x2 v = {lo, hi}; bf16x2_t b = __builtin_convertvector(v, bf16x2_t); return __builtin_bit_cast(unsigned, b); }
; DI float bflo(unsigned w) { return __uint_as_float(w << 16); }
; DI float bfhi(unsigned w) { return __uint_as_float(w & 0xffff0000u); }
; DI float geluf_(float x) { const float a = 0.7978845608028654f * (x + 0.044715f * x * x * x); const float t = 1.f - 2.f * __builtin_amdgcn_rcpf(__expf(2.f * a) + 1.f); return 0.5f * x * (1.f + t); }
; #define MFMA16(a, b, c) __builtin_amdgcn_mfma_f32_16x16x32_bf16((a), (b), (c), 0, 0, 0)
; DI void ssm_step_lds(const SsmC& c, const LAS bf16_t* up_, float& xr, float& xi) {
;     const LAS f32x4* up = (const LAS f32x4*)up_;
;     const f32x4 u0 = up[0], u1 = up[1], u2 = up[2], u3 = up[3];
;     float sr = 0.f, si = 0.f;
; #pragma unroll
;     for (int e = 0; e < 4; ++e) { sr += c.bbr[e] * u0[e]; si += c.bbi[e] * u0[e]; }
; #pragma unroll
;     for (int e = 0; e < 4; ++e) { sr += c.bbr[4 + e] * u1[e]; si += c.bbi[4 + e] * u1[e]; }
; #pragma unroll
;     for (int e = 0; e < 4; ++e) { sr += c.bbr[8 + e] * u2[e]; si += c.bbi[8 + e] * u2[e]; }
; #pragma unroll
;     for (int e = 0; e < 4; ++e) { sr += c.bbr[12 + e] * u3[e]; si += c.bbi[12 + e] * u3[e]; }
;     const float nxr = c.ar * xr - c.ai * xi + sr, nxi = c.ar * xi + c.ai * xr + si; xr = nxr; xi = nxi;
; }
; DI void ssm_s3(CArgs& a, int l, int it, int lane, LAS bf16_t* Xs  , LAS bf16_t* Us) {
;     ...
;         for (int m = 0; m < 2; ++m) {
;             float zz = 0.f; asm volatile("" : "+v"(zz)); f32x4 acc = {zz, zz, zz, zz};
; #pragma unroll
;             for (int kk = 0; kk < 4; ++kk) { const bf16x8 xf = lds_b128(Xs + (16 * m + fr) * 136 + 32 * kk + 8 * fq); acc = MFMA16(cf[kk], xf, acc); }
;             const size_t tg = t0 + 32 * sub + 16 * m + fr;
;             const u32x2 uw = *(const u32x2*)(zb + tg * NZ + ZU + g * 16 + 4 * fq);
;             const float y0 = geluf_(acc[0] + dsk[0] * bflo(uw.x)), y1 = geluf_(acc[1] + dsk[1] * bfhi(uw.x)), y2 = geluf_(acc[2] + dsk[2] * bflo(uw.y)), y3 = geluf_(acc[3] + dsk[3] * bfhi(uw.y));
;             u32x2 ow; ow.x = pk2(y0, y1); ow.y = pk2(y2, y3);
;             *(u32x2*)(gb + tg * 512 + g * 16 + 4 * fq) = ow;
	s_nop 0
	v_mfma_f32_16x16x32_bf16 v[30:33], v[4:7], v[34:37], v[30:33]
	ds_read_b128 v[34:37], v126 offset:4416
	s_waitcnt lgkmcnt(0)
	v_mfma_f32_16x16x32_bf16 v[30:33], v[8:11], v[34:37], v[30:33]
	ds_read_b128 v[34:37], v126 offset:4480
	s_waitcnt lgkmcnt(0)
	v_mfma_f32_16x16x32_bf16 v[30:33], v[12:15], v[34:37], v[30:33]
	ds_read_b128 v[34:37], v126 offset:4544
	s_waitcnt lgkmcnt(0)
	v_mfma_f32_16x16x32_bf16 v[30:33], v[16:19], v[34:37], v[30:33]
	s_waitcnt vmcnt(4)
	v_mov_b32_e32 v22, v238
	v_mov_b32_e32 v23, v239
	v_lshlrev_b32_e32 v34, 16, v22
	v_and_b32_e32 v35, 0xffff0000, v22
	s_nop 4
	v_pk_fma_f32 v[30:31], v[0:1], v[34:35], v[30:31]
	s_nop 0
	v_mul_f32_e32 v22, 0x3d372713, v30
	v_mul_f32_e32 v22, v30, v22
	v_fma_f32 v22, v30, v22, v30
	v_mul_f32_e32 v22, 0x3f4c422a, v22
	v_add_f32_e32 v22, v22, v22
	v_mul_f32_e32 v22, 0x3fb8aa3b, v22
	v_exp_f32_e32 v22, v22
	s_nop 0
	v_add_f32_e32 v22, 1.0, v22
	v_rcp_f32_e32 v34, v22
	v_mul_f32_e32 v22, 0x3d372713, v31
	v_mul_f32_e32 v22, v31, v22
	v_fma_f32 v22, v31, v22, v31
	v_mul_f32_e32 v22, 0x3f4c422a, v22
	v_add_f32_e32 v22, v22, v22
	v_mul_f32_e32 v22, 0x3fb8aa3b, v22
	v_exp_f32_e32 v22, v22
	v_pk_mul_f32 v[30:31], v[30:31], 0.5 op_sel_hi:[1,0]
	v_add_f32_e32 v22, 1.0, v22
	v_rcp_f32_e32 v35, v22
	v_lshlrev_b32_e32 v22, 16, v23
	v_and_b32_e32 v23, 0xffff0000, v23
	v_pk_fma_f32 v[22:23], v[2:3], v[22:23], v[32:33]
	v_pk_fma_f32 v[34:35], v[34:35], 2.0, 1.0 op_sel_hi:[1,0,0] neg_lo:[1,0,0] neg_hi:[1,0,0]
	v_mul_f32_e32 v32, 0x3d372713, v22
	v_mul_f32_e32 v33, 0x3d372713, v23
	v_mul_f32_e32 v32, v22, v32
	v_mul_f32_e32 v33, v23, v33
	v_fma_f32 v32, v22, v32, v22
	v_fma_f32 v33, v23, v33, v23
	v_mul_f32_e32 v32, 0x3f4c422a, v32
	v_mul_f32_e32 v33, 0x3f4c422a, v33
	v_add_f32_e32 v32, v32, v32
	v_add_f32_e32 v33, v33, v33
	v_mul_f32_e32 v32, 0x3fb8aa3b, v32
	v_mul_f32_e32 v33, 0x3fb8aa3b, v33
	v_exp_f32_e32 v32, v32
	v_exp_f32_e32 v33, v33
	v_pk_add_f32 v[34:35], v[34:35], 1.0 op_sel_hi:[1,0]
	v_pk_mul_f32 v[22:23], v[22:23], 0.5 op_sel_hi:[1,0]
	v_add_f32_e32 v32, 1.0, v32
	v_add_f32_e32 v33, 1.0, v33
	v_rcp_f32_e32 v32, v32
	v_rcp_f32_e32 v33, v33
	v_pk_mul_f32 v[30:31], v[30:31], v[34:35]
	v_pk_fma_f32 v[32:33], v[32:33], 2.0, 1.0 op_sel_hi:[1,0,0] neg_lo:[1,0,0] neg_hi:[1,0,0]
	s_nop 0
	v_pk_add_f32 v[32:33], v[32:33], 1.0 op_sel_hi:[1,0]
	s_nop 0
	v_pk_mul_f32 v[32:33], v[22:23], v[32:33]
	v_cvt_pk_bf16_f32 v22, v30, v31
	v_or_b32_e32 v30, 0xc000, v20
	v_mov_b32_e32 v31, v21
	v_cvt_pk_bf16_f32 v23, v32, v33
	v_lshl_add_u64 v[30:31], v[24:25], 0, v[30:31]
	global_store_dwordx2 v[30:31], v[22:23], off
	s_waitcnt lgkmcnt(0)
	v_mov_b32_e32 v22, v124
.LBB0_184:
	s_add_i32 s3, s0, s1
	s_add_i32 s4, s3, 0x12800
	v_mov_b32_e32 v23, s4
	ds_read_b128 v[30:33], v23
	s_add_i32 s4, s3, 0x12810
	v_mov_b32_e32 v23, s4
	ds_read_b128 v[34:37], v23
	s_add_i32 s4, s3, 0x12820
	s_waitcnt lgkmcnt(1)
	v_pk_fma_f32 v[48:49], v[74:75], v[30:31], 0 op_sel_hi:[1,0,0]
	v_mov_b32_e32 v23, s4
	v_pk_fma_f32 v[30:31], v[76:77], v[30:31], v[48:49] op_sel:[0,1,0]
	ds_read_b128 v[40:43], v23
	v_pk_fma_f32 v[30:31], v[78:79], v[32:33], v[30:31] op_sel_hi:[1,0,1]
	v_pk_fma_f32 v[30:31], v[98:99], v[32:33], v[30:31] op_sel:[0,1,0]
	s_add_i32 s4, s3, 0x12830
	s_waitcnt lgkmcnt(1)
	v_pk_fma_f32 v[30:31], v[100:101], v[34:35], v[30:31] op_sel_hi:[1,0,1]
	v_mov_b32_e32 v23, s4
	v_pk_fma_f32 v[30:31], v[102:103], v[34:35], v[30:31] op_sel:[0,1,0]
	v_pk_fma_f32 v[30:31], v[104:105], v[36:37], v[30:31] op_sel_hi:[1,0,1]
	ds_read_b128 v[44:47], v23
	v_pk_fma_f32 v[30:31], v[106:107], v[36:37], v[30:31] op_sel:[0,1,0]
	s_waitcnt lgkmcnt(1)
	v_pk_fma_f32 v[30:31], v[108:109], v[40:41], v[30:31] op_sel_hi:[1,0,1]
	v_pk_mul_f32 v[32:33], v[72:73], v[38:39]
	v_pk_fma_f32 v[30:31], v[110:111], v[40:41], v[30:31] op_sel:[0,1,0]
	s_add_i32 s4, s3, 0x12840
	v_pk_fma_f32 v[30:31], v[112:113], v[42:43], v[30:31] op_sel_hi:[1,0,1]
	s_addk_i32 s1, 0x100
	v_pk_fma_f32 v[30:31], v[114:115], v[42:43], v[30:31] op_sel:[0,1,0]
	s_waitcnt lgkmcnt(0)
	v_pk_fma_f32 v[30:31], v[116:117], v[44:45], v[30:31] op_sel_hi:[1,0,1]
	s_nop 0
	v_pk_fma_f32 v[30:31], v[118:119], v[44:45], v[30:31] op_sel:[0,1,0]
	s_nop 0
	v_pk_fma_f32 v[30:31], v[120:121], v[46:47], v[30:31] op_sel_hi:[1,0,1]
	s_nop 0
	v_pk_fma_f32 v[30:31], v[122:123], v[46:47], v[30:31] op_sel:[0,1,0]
	v_pk_fma_f32 v[34:35], v[70:71], v[38:39], v[32:33] op_sel:[0,0,1] op_sel_hi:[1,1,0]
	v_pk_fma_f32 v[32:33], v[70:71], v[38:39], v[32:33] op_sel:[0,0,1] op_sel_hi:[1,1,0] neg_lo:[0,0,1] neg_hi:[0,0,1]
	s_nop 0
	v_mov_b32_e32 v35, v33
	v_pk_add_f32 v[46:47], v[34:35], v[30:31]
	s_nop 0
	v_bfe_u32 v23, v47, 16, 1
	v_add3_u32 v23, v47, v23, s33
	ds_write_b16_d16_hi v22, v23
	v_bfe_u32 v23, v46, 16, 1
	v_add3_u32 v23, v46, v23, s33
	ds_write_b16_d16_hi v22, v23 offset:128
	v_mov_b32_e32 v23, s4
	ds_read_b128 v[30:33], v23
	s_add_i32 s4, s3, 0x12850
	v_mov_b32_e32 v23, s4
	ds_read_b128 v[34:37], v23
	s_add_i32 s4, s3, 0x12860
	s_waitcnt lgkmcnt(1)
	v_pk_fma_f32 v[48:49], v[74:75], v[30:31], 0 op_sel_hi:[1,0,0]
	v_mov_b32_e32 v23, s4
	v_pk_fma_f32 v[30:31], v[76:77], v[30:31], v[48:49] op_sel:[0,1,0]
	ds_read_b128 v[38:41], v23
	v_pk_fma_f32 v[30:31], v[78:79], v[32:33], v[30:31] op_sel_hi:[1,0,1]
	v_pk_fma_f32 v[30:31], v[98:99], v[32:33], v[30:31] op_sel:[0,1,0]
	s_add_i32 s4, s3, 0x12870
	s_waitcnt lgkmcnt(1)
	v_pk_fma_f32 v[30:31], v[100:101], v[34:35], v[30:31] op_sel_hi:[1,0,1]
	v_mov_b32_e32 v23, s4
	v_pk_fma_f32 v[30:31], v[102:103], v[34:35], v[30:31] op_sel:[0,1,0]
	v_pk_fma_f32 v[30:31], v[104:105], v[36:37], v[30:31] op_sel_hi:[1,0,1]
	ds_read_b128 v[42:45], v23
	v_pk_fma_f32 v[30:31], v[106:107], v[36:37], v[30:31] op_sel:[0,1,0]
	s_waitcnt lgkmcnt(1)
; #define LAS __attribute__((address_space(3)))
; DI unsigned f2bf(float f) { unsigned u = __builtin_bit_cast(unsigned, f); return (u + 0x7fffu + ((u >> 16) & 1u)) >> 16; }
; DI void ssm_step_lds(const SsmC& c, const LAS bf16_t* up_, float& xr, float& xi) {
;     const LAS f32x4* up = (const LAS f32x4*)up_;
;     const f32x4 u0 = up[0], u1 = up[1], u2 = up[2], u3 = up[3];
;     float sr = 0.f, si = 0.f;
; #pragma unroll
;     for (int e = 0; e < 4; ++e) { sr += c.bbr[e] * u0[e]; si += c.bbi[e] * u0[e]; }
; #pragma unroll
;     for (int e = 0; e < 4; ++e) { sr += c.bbr[4 + e] * u1[e]; si += c.bbi[4 + e] * u1[e]; }
; #pragma unroll
;     for (int e = 0; e < 4; ++e) { sr += c.bbr[8 + e] * u2[e]; si += c.bbi[8 + e] * u2[e]; }
; #pragma unroll
;     for (int e = 0; e < 4; ++e) { sr += c.bbr[12 + e] * u3[e]; si += c.bbi[12 + e] * u3[e]; }
;     const float nxr = c.ar * xr - c.ai * xi + sr, nxi = c.ar * xi + c.ai * xr + si; xr = nxr; xi = nxi;
; }
; DI void ssm_s3(CArgs& a, int l, int it, int lane, LAS bf16_t* Xs  , LAS bf16_t* Us) {
;     ...
;     for (int sub = 0; sub < 4; ++sub) {
; #pragma unroll 4
;         for (int tt = 0; tt < 32; ++tt) { ssm_step_lds(c, Us + (32 * sub + tt) * 32, xr, xi);
;             Xs[tt * 136 + lane] = (bf16_t)f2bf(xr); Xs[tt * 136 + 64 + lane] = (bf16_t)f2bf(xi); }
	v_pk_fma_f32 v[30:31], v[108:109], v[38:39], v[30:31] op_sel_hi:[1,0,1]
	v_pk_mul_f32 v[32:33], v[72:73], v[46:47]
	v_pk_fma_f32 v[30:31], v[110:111], v[38:39], v[30:31] op_sel:[0,1,0]
	s_add_i32 s4, s3, 0x12880
	v_pk_fma_f32 v[30:31], v[112:113], v[40:41], v[30:31] op_sel_hi:[1,0,1]
	s_nop 0
	v_pk_fma_f32 v[30:31], v[114:115], v[40:41], v[30:31] op_sel:[0,1,0]
	s_waitcnt lgkmcnt(0)
	v_pk_fma_f32 v[30:31], v[116:117], v[42:43], v[30:31] op_sel_hi:[1,0,1]
	s_nop 0
	v_pk_fma_f32 v[30:31], v[118:119], v[42:43], v[30:31] op_sel:[0,1,0]
	s_nop 0
	v_pk_fma_f32 v[30:31], v[120:121], v[44:45], v[30:31] op_sel_hi:[1,0,1]
	s_nop 0
	v_pk_fma_f32 v[30:31], v[122:123], v[44:45], v[30:31] op_sel:[0,1,0]
	v_pk_fma_f32 v[34:35], v[70:71], v[46:47], v[32:33] op_sel:[0,0,1] op_sel_hi:[1,1,0]
	v_pk_fma_f32 v[32:33], v[70:71], v[46:47], v[32:33] op_sel:[0,0,1] op_sel_hi:[1,1,0] neg_lo:[0,0,1] neg_hi:[0,0,1]
	s_nop 0
	v_mov_b32_e32 v35, v33
	v_pk_add_f32 v[46:47], v[34:35], v[30:31]
	s_nop 0
	v_bfe_u32 v23, v47, 16, 1
	v_add3_u32 v23, v47, v23, s33
	ds_write_b16_d16_hi v22, v23 offset:272
	v_bfe_u32 v23, v46, 16, 1
	v_add3_u32 v23, v46, v23, s33
	ds_write_b16_d16_hi v22, v23 offset:400
	v_mov_b32_e32 v23, s4
	ds_read_b128 v[30:33], v23
	s_add_i32 s4, s3, 0x12890
	v_mov_b32_e32 v23, s4
	ds_read_b128 v[34:37], v23
	s_add_i32 s4, s3, 0x128a0
	s_waitcnt lgkmcnt(1)
	v_pk_fma_f32 v[48:49], v[74:75], v[30:31], 0 op_sel_hi:[1,0,0]
	v_mov_b32_e32 v23, s4
	v_pk_fma_f32 v[30:31], v[76:77], v[30:31], v[48:49] op_sel:[0,1,0]
	ds_read_b128 v[38:41], v23
	v_pk_fma_f32 v[30:31], v[78:79], v[32:33], v[30:31] op_sel_hi:[1,0,1]
	v_pk_fma_f32 v[30:31], v[98:99], v[32:33], v[30:31] op_sel:[0,1,0]
	s_add_i32 s4, s3, 0x128b0
	s_waitcnt lgkmcnt(1)
	v_pk_fma_f32 v[30:31], v[100:101], v[34:35], v[30:31] op_sel_hi:[1,0,1]
	v_mov_b32_e32 v23, s4
	v_pk_fma_f32 v[30:31], v[102:103], v[34:35], v[30:31] op_sel:[0,1,0]
	v_pk_fma_f32 v[30:31], v[104:105], v[36:37], v[30:31] op_sel_hi:[1,0,1]
	ds_read_b128 v[42:45], v23
	v_pk_fma_f32 v[30:31], v[106:107], v[36:37], v[30:31] op_sel:[0,1,0]
	s_waitcnt lgkmcnt(1)
	v_pk_fma_f32 v[30:31], v[108:109], v[38:39], v[30:31] op_sel_hi:[1,0,1]
	v_pk_mul_f32 v[32:33], v[72:73], v[46:47]
	v_pk_fma_f32 v[30:31], v[110:111], v[38:39], v[30:31] op_sel:[0,1,0]
	s_add_i32 s4, s3, 0x128c0
	v_pk_fma_f32 v[30:31], v[112:113], v[40:41], v[30:31] op_sel_hi:[1,0,1]
	s_nop 0
	v_pk_fma_f32 v[30:31], v[114:115], v[40:41], v[30:31] op_sel:[0,1,0]
	s_waitcnt lgkmcnt(0)
	v_pk_fma_f32 v[30:31], v[116:117], v[42:43], v[30:31] op_sel_hi:[1,0,1]
	s_nop 0
	v_pk_fma_f32 v[30:31], v[118:119], v[42:43], v[30:31] op_sel:[0,1,0]
	s_nop 0
	v_pk_fma_f32 v[30:31], v[120:121], v[44:45], v[30:31] op_sel_hi:[1,0,1]
	s_nop 0
	v_pk_fma_f32 v[30:31], v[122:123], v[44:45], v[30:31] op_sel:[0,1,0]
	v_pk_fma_f32 v[34:35], v[70:71], v[46:47], v[32:33] op_sel:[0,0,1] op_sel_hi:[1,1,0]
	v_pk_fma_f32 v[32:33], v[70:71], v[46:47], v[32:33] op_sel:[0,0,1] op_sel_hi:[1,1,0] neg_lo:[0,0,1] neg_hi:[0,0,1]
	s_nop 0
	v_mov_b32_e32 v35, v33
	v_pk_add_f32 v[46:47], v[34:35], v[30:31]
	s_nop 0
	v_bfe_u32 v23, v47, 16, 1
	v_add3_u32 v23, v47, v23, s33
	ds_write_b16_d16_hi v22, v23 offset:544
	v_bfe_u32 v23, v46, 16, 1
	v_add3_u32 v23, v46, v23, s33
	ds_write_b16_d16_hi v22, v23 offset:672
	v_mov_b32_e32 v23, s4
	ds_read_b128 v[30:33], v23
	s_add_i32 s4, s3, 0x128d0
	v_mov_b32_e32 v23, s4
	ds_read_b128 v[34:37], v23
	s_add_i32 s4, s3, 0x128e0
	s_waitcnt lgkmcnt(1)
	v_pk_fma_f32 v[48:49], v[74:75], v[30:31], 0 op_sel_hi:[1,0,0]
	v_mov_b32_e32 v23, s4
	v_pk_fma_f32 v[30:31], v[76:77], v[30:31], v[48:49] op_sel:[0,1,0]
	ds_read_b128 v[38:41], v23
	v_pk_fma_f32 v[30:31], v[78:79], v[32:33], v[30:31] op_sel_hi:[1,0,1]
	v_pk_fma_f32 v[30:31], v[98:99], v[32:33], v[30:31] op_sel:[0,1,0]
	s_add_i32 s3, s3, 0x128f0
	s_waitcnt lgkmcnt(1)
	v_pk_fma_f32 v[30:31], v[100:101], v[34:35], v[30:31] op_sel_hi:[1,0,1]
	v_mov_b32_e32 v23, s3
	v_pk_fma_f32 v[30:31], v[102:103], v[34:35], v[30:31] op_sel:[0,1,0]
	v_pk_fma_f32 v[30:31], v[104:105], v[36:37], v[30:31] op_sel_hi:[1,0,1]
	ds_read_b128 v[42:45], v23
	v_pk_fma_f32 v[30:31], v[106:107], v[36:37], v[30:31] op_sel:[0,1,0]
	s_waitcnt lgkmcnt(1)
	v_pk_fma_f32 v[30:31], v[108:109], v[38:39], v[30:31] op_sel_hi:[1,0,1]
	v_pk_mul_f32 v[32:33], v[72:73], v[46:47]
	v_pk_fma_f32 v[30:31], v[110:111], v[38:39], v[30:31] op_sel:[0,1,0]
	s_cmp_lg_u32 s1, 0
	v_pk_fma_f32 v[30:31], v[112:113], v[40:41], v[30:31] op_sel_hi:[1,0,1]
	s_nop 0
	v_pk_fma_f32 v[30:31], v[114:115], v[40:41], v[30:31] op_sel:[0,1,0]
	s_waitcnt lgkmcnt(0)
	v_pk_fma_f32 v[30:31], v[116:117], v[42:43], v[30:31] op_sel_hi:[1,0,1]
	s_nop 0
	v_pk_fma_f32 v[30:31], v[118:119], v[42:43], v[30:31] op_sel:[0,1,0]
	s_nop 0
	v_pk_fma_f32 v[30:31], v[120:121], v[44:45], v[30:31] op_sel_hi:[1,0,1]
	s_nop 0
	v_pk_fma_f32 v[30:31], v[122:123], v[44:45], v[30:31] op_sel:[0,1,0]
	v_pk_fma_f32 v[34:35], v[70:71], v[46:47], v[32:33] op_sel:[0,0,1] op_sel_hi:[1,1,0]
	v_pk_fma_f32 v[32:33], v[70:71], v[46:47], v[32:33] op_sel:[0,0,1] op_sel_hi:[1,1,0] neg_lo:[0,0,1] neg_hi:[0,0,1]
	s_nop 0
	v_mov_b32_e32 v35, v33
	v_pk_add_f32 v[38:39], v[34:35], v[30:31]
	s_nop 0
	v_bfe_u32 v23, v39, 16, 1
	v_add3_u32 v23, v39, v23, s33
	ds_write_b16_d16_hi v22, v23 offset:816
	v_bfe_u32 v23, v38, 16, 1
	v_add3_u32 v23, v38, v23, s33
	ds_write_b16_d16_hi v22, v23 offset:944
	v_add_u32_e32 v22, 0x440, v22
	s_cbranch_scc1 .LBB0_184
; DI unsigned pk2(float lo, float hi) { f32x2 v = {lo, hi}; bf16x2_t b = __builtin_convertvector(v, bf16x2_t); return __builtin_bit_cast(unsigned, b); }
; DI float bflo(unsigned w) { return __uint_as_float(w << 16); }
; DI float bfhi(unsigned w) { return __uint_as_float(w & 0xffff0000u); }
; DI float geluf_(float x) { const float a = 0.7978845608028654f * (x + 0.044715f * x * x * x); const float t = 1.f - 2.f * __builtin_amdgcn_rcpf(__expf(2.f * a) + 1.f); return 0.5f * x * (1.f + t); }
; #define MFMA16(a, b, c) __builtin_amdgcn_mfma_f32_16x16x32_bf16((a), (b), (c), 0, 0, 0)
; DI void ssm_s3(CArgs& a, int l, int it, int lane, LAS bf16_t* Xs  , LAS bf16_t* Us) {
;     ...
;         for (int m = 0; m < 2; ++m) {
;             float zz = 0.f; asm volatile("" : "+v"(zz)); f32x4 acc = {zz, zz, zz, zz};
; #pragma unroll
;             for (int kk = 0; kk < 4; ++kk) { const bf16x8 xf = lds_b128(Xs + (16 * m + fr) * 136 + 32 * kk + 8 * fq); acc = MFMA16(cf[kk], xf, acc); }
;             const size_t tg = t0 + 32 * sub + 16 * m + fr;
;             const u32x2 uw = *(const u32x2*)(zb + tg * NZ + ZU + g * 16 + 4 * fq);
;             const float y0 = geluf_(acc[0] + dsk[0] * bflo(uw.x)), y1 = geluf_(acc[1] + dsk[1] * bfhi(uw.x)), y2 = geluf_(acc[2] + dsk[2] * bflo(uw.y)), y3 = geluf_(acc[3] + dsk[3] * bfhi(uw.y));
;             u32x2 ow; ow.x = pk2(y0, y1); ow.y = pk2(y2, y3);
;             *(u32x2*)(gb + tg * 512 + g * 16 + 4 * fq) = ow;
	v_mov_b32_e32 v30, v81
	s_waitcnt lgkmcnt(0)
	ds_read_b128 v[34:37], v126
	v_mov_b32_e32 v31, v30
	v_mov_b32_e32 v32, v30
	v_mov_b32_e32 v33, v30
	v_or_b32_e32 v40, 64, v26
	v_mad_u64_u32 v[22:23], s[4:5], v40, s55, v[28:29]
	s_waitcnt lgkmcnt(0)
	v_mfma_f32_16x16x32_bf16 v[30:33], v[4:7], v[34:37], v[30:33]
	ds_read_b128 v[34:37], v126 offset:64
	v_mad_i32_i24 v23, v27, s55, v23
	v_mov_b32_e32 v41, v27
	s_waitcnt lgkmcnt(0)
	v_mfma_f32_16x16x32_bf16 v[30:33], v[8:11], v[34:37], v[30:33]
	ds_read_b128 v[34:37], v126 offset:128
	s_movk_i32 s1, 0xf800
	s_waitcnt lgkmcnt(0)
	v_mfma_f32_16x16x32_bf16 v[30:33], v[12:15], v[34:37], v[30:33]
	ds_read_b128 v[34:37], v126 offset:192
	s_waitcnt lgkmcnt(0)
	v_mfma_f32_16x16x32_bf16 v[30:33], v[16:19], v[34:37], v[30:33]
	v_add_co_u32_e32 v22, vcc, s79, v22
	s_waitcnt vmcnt(3)
	v_mov_b32_e32 v34, v240
	v_mov_b32_e32 v35, v241
	v_lshlrev_b32_e32 v36, 16, v34
	v_and_b32_e32 v37, 0xffff0000, v34
	s_nop 2
	v_pk_fma_f32 v[30:31], v[0:1], v[36:37], v[30:31]
	v_addc_co_u32_e32 v23, vcc, 0, v23, vcc
	v_mul_f32_e32 v34, 0x3d372713, v30
	v_mul_f32_e32 v34, v30, v34
	v_fma_f32 v34, v30, v34, v30
	v_mul_f32_e32 v34, 0x3f4c422a, v34
	v_add_f32_e32 v34, v34, v34
	v_mul_f32_e32 v34, 0x3fb8aa3b, v34
	v_exp_f32_e32 v34, v34
	s_nop 0
	v_add_f32_e32 v34, 1.0, v34
	v_rcp_f32_e32 v36, v34
	v_mul_f32_e32 v34, 0x3d372713, v31
	v_mul_f32_e32 v34, v31, v34
	v_fma_f32 v34, v31, v34, v31
	v_mul_f32_e32 v34, 0x3f4c422a, v34
	v_add_f32_e32 v34, v34, v34
	v_mul_f32_e32 v34, 0x3fb8aa3b, v34
	v_exp_f32_e32 v34, v34
	v_pk_mul_f32 v[30:31], v[30:31], 0.5 op_sel_hi:[1,0]
	v_add_f32_e32 v34, 1.0, v34
	v_rcp_f32_e32 v37, v34
	v_lshlrev_b32_e32 v34, 16, v35
	v_and_b32_e32 v35, 0xffff0000, v35
	v_pk_fma_f32 v[32:33], v[2:3], v[34:35], v[32:33]
	v_pk_fma_f32 v[36:37], v[36:37], 2.0, 1.0 op_sel_hi:[1,0,0] neg_lo:[1,0,0] neg_hi:[1,0,0]
	v_mul_f32_e32 v34, 0x3d372713, v32
	v_mul_f32_e32 v35, 0x3d372713, v33
	v_mul_f32_e32 v34, v32, v34
	v_mul_f32_e32 v35, v33, v35
	v_fma_f32 v34, v32, v34, v32
	v_fma_f32 v35, v33, v35, v33
	v_mul_f32_e32 v34, 0x3f4c422a, v34
	v_mul_f32_e32 v35, 0x3f4c422a, v35
	v_add_f32_e32 v34, v34, v34
	v_add_f32_e32 v35, v35, v35
	v_mul_f32_e32 v34, 0x3fb8aa3b, v34
	v_mul_f32_e32 v35, 0x3fb8aa3b, v35
	v_exp_f32_e32 v34, v34
	v_exp_f32_e32 v35, v35
	v_pk_add_f32 v[36:37], v[36:37], 1.0 op_sel_hi:[1,0]
	v_pk_mul_f32 v[32:33], v[32:33], 0.5 op_sel_hi:[1,0]
	v_add_f32_e32 v34, 1.0, v34
	v_add_f32_e32 v35, 1.0, v35
	v_rcp_f32_e32 v34, v34
	v_rcp_f32_e32 v35, v35
	v_pk_mul_f32 v[30:31], v[30:31], v[36:37]
	v_pk_fma_f32 v[34:35], v[34:35], 2.0, 1.0 op_sel_hi:[1,0,0] neg_lo:[1,0,0] neg_hi:[1,0,0]
	s_nop 0
	v_pk_add_f32 v[34:35], v[34:35], 1.0 op_sel_hi:[1,0]
	v_cvt_pk_bf16_f32 v30, v30, v31
	v_pk_mul_f32 v[32:33], v[32:33], v[34:35]
	s_nop 0
	v_cvt_pk_bf16_f32 v31, v32, v33
	v_lshlrev_b64 v[32:33], 10, v[40:41]
	v_lshl_add_u64 v[32:33], v[24:25], 0, v[32:33]
	global_store_dwordx2 v[32:33], v[30:31], off
	v_mov_b32_e32 v30, v81
	ds_read_b128 v[34:37], v126 offset:4352
	v_mov_b32_e32 v31, v30
	v_mov_b32_e32 v32, v30
	v_mov_b32_e32 v33, v30
	s_waitcnt lgkmcnt(0)
	s_nop 0
	v_mfma_f32_16x16x32_bf16 v[30:33], v[4:7], v[34:37], v[30:33]
	ds_read_b128 v[34:37], v126 offset:4416
	s_waitcnt lgkmcnt(0)
	v_mfma_f32_16x16x32_bf16 v[30:33], v[8:11], v[34:37], v[30:33]
	ds_read_b128 v[34:37], v126 offset:4480
	s_waitcnt lgkmcnt(0)
	v_mfma_f32_16x16x32_bf16 v[30:33], v[12:15], v[34:37], v[30:33]
	ds_read_b128 v[34:37], v126 offset:4544
	s_waitcnt lgkmcnt(0)
	v_mfma_f32_16x16x32_bf16 v[30:33], v[16:19], v[34:37], v[30:33]
	s_waitcnt vmcnt(2)
	v_mov_b32_e32 v22, v242
	v_mov_b32_e32 v23, v243
	v_lshlrev_b32_e32 v34, 16, v22
	v_and_b32_e32 v35, 0xffff0000, v22
	s_nop 4
	v_pk_fma_f32 v[30:31], v[0:1], v[34:35], v[30:31]
	s_nop 0
	v_mul_f32_e32 v22, 0x3d372713, v30
	v_mul_f32_e32 v22, v30, v22
	v_fma_f32 v22, v30, v22, v30
	v_mul_f32_e32 v22, 0x3f4c422a, v22
	v_add_f32_e32 v22, v22, v22
	v_mul_f32_e32 v22, 0x3fb8aa3b, v22
	v_exp_f32_e32 v22, v22
	s_nop 0
	v_add_f32_e32 v22, 1.0, v22
	v_rcp_f32_e32 v34, v22
	v_mul_f32_e32 v22, 0x3d372713, v31
	v_mul_f32_e32 v22, v31, v22
	v_fma_f32 v22, v31, v22, v31
	v_mul_f32_e32 v22, 0x3f4c422a, v22
	v_add_f32_e32 v22, v22, v22
	v_mul_f32_e32 v22, 0x3fb8aa3b, v22
	v_exp_f32_e32 v22, v22
	v_pk_mul_f32 v[30:31], v[30:31], 0.5 op_sel_hi:[1,0]
	v_add_f32_e32 v22, 1.0, v22
	v_rcp_f32_e32 v35, v22
	v_lshlrev_b32_e32 v22, 16, v23
	v_and_b32_e32 v23, 0xffff0000, v23
	v_pk_fma_f32 v[22:23], v[2:3], v[22:23], v[32:33]
	v_pk_fma_f32 v[34:35], v[34:35], 2.0, 1.0 op_sel_hi:[1,0,0] neg_lo:[1,0,0] neg_hi:[1,0,0]
	v_mul_f32_e32 v32, 0x3d372713, v22
	v_mul_f32_e32 v33, 0x3d372713, v23
	v_mul_f32_e32 v32, v22, v32
	v_mul_f32_e32 v33, v23, v33
	v_fma_f32 v32, v22, v32, v22
	v_fma_f32 v33, v23, v33, v23
	v_mul_f32_e32 v32, 0x3f4c422a, v32
	v_mul_f32_e32 v33, 0x3f4c422a, v33
	v_add_f32_e32 v32, v32, v32
	v_add_f32_e32 v33, v33, v33
	v_mul_f32_e32 v32, 0x3fb8aa3b, v32
	v_mul_f32_e32 v33, 0x3fb8aa3b, v33
	v_exp_f32_e32 v32, v32
	v_exp_f32_e32 v33, v33
	v_pk_add_f32 v[34:35], v[34:35], 1.0 op_sel_hi:[1,0]
	v_pk_mul_f32 v[22:23], v[22:23], 0.5 op_sel_hi:[1,0]
	v_add_f32_e32 v32, 1.0, v32
	v_add_f32_e32 v33, 1.0, v33
	v_rcp_f32_e32 v32, v32
	v_rcp_f32_e32 v33, v33
	v_pk_mul_f32 v[30:31], v[30:31], v[34:35]
	v_pk_fma_f32 v[32:33], v[32:33], 2.0, 1.0 op_sel_hi:[1,0,0] neg_lo:[1,0,0] neg_hi:[1,0,0]
	s_nop 0
	v_pk_add_f32 v[32:33], v[32:33], 1.0 op_sel_hi:[1,0]
	s_nop 0
	v_pk_mul_f32 v[32:33], v[22:23], v[32:33]
	v_cvt_pk_bf16_f32 v22, v30, v31
	v_or_b32_e32 v30, 0x14000, v20
	v_mov_b32_e32 v31, v21
	v_cvt_pk_bf16_f32 v23, v32, v33
	v_lshl_add_u64 v[30:31], v[24:25], 0, v[30:31]
	global_store_dwordx2 v[30:31], v[22:23], off
	s_waitcnt lgkmcnt(0)
	v_mov_b32_e32 v22, v124
; #define LAS __attribute__((address_space(3)))
; DI unsigned f2bf(float f) { unsigned u = __builtin_bit_cast(unsigned, f); return (u + 0x7fffu + ((u >> 16) & 1u)) >> 16; }
; DI void ssm_step_lds(const SsmC& c, const LAS bf16_t* up_, float& xr, float& xi) {
;     const LAS f32x4* up = (const LAS f32x4*)up_;
;     const f32x4 u0 = up[0], u1 = up[1], u2 = up[2], u3 = up[3];
;     float sr = 0.f, si = 0.f;
; #pragma unroll
;     for (int e = 0; e < 4; ++e) { sr += c.bbr[e] * u0[e]; si += c.bbi[e] * u0[e]; }
; #pragma unroll
;     for (int e = 0; e < 4; ++e) { sr += c.bbr[4 + e] * u1[e]; si += c.bbi[4 + e] * u1[e]; }
; #pragma unroll
;     for (int e = 0; e < 4; ++e) { sr += c.bbr[8 + e] * u2[e]; si += c.bbi[8 + e] * u2[e]; }
; #pragma unroll
;     for (int e = 0; e < 4; ++e) { sr += c.bbr[12 + e] * u3[e]; si += c.bbi[12 + e] * u3[e]; }
;     const float nxr = c.ar * xr - c.ai * xi + sr, nxi = c.ar * xi + c.ai * xr + si; xr = nxr; xi = nxi;
; }
; DI void ssm_s3(CArgs& a, int l, int it, int lane, LAS bf16_t* Xs  , LAS bf16_t* Us) {
;     ...
;     for (int sub = 0; sub < 4; ++sub) {
; #pragma unroll 4
;         for (int tt = 0; tt < 32; ++tt) { ssm_step_lds(c, Us + (32 * sub + tt) * 32, xr, xi);
;             Xs[tt * 136 + lane] = (bf16_t)f2bf(xr); Xs[tt * 136 + 64 + lane] = (bf16_t)f2bf(xi); }
.LBB0_186:
	s_add_i32 s3, s0, s1
	s_add_i32 s4, s3, 0x13000
	v_mov_b32_e32 v23, s4
	ds_read_b128 v[30:33], v23
	s_add_i32 s4, s3, 0x13010
	v_mov_b32_e32 v23, s4
	ds_read_b128 v[34:37], v23
	s_add_i32 s4, s3, 0x13020
	s_waitcnt lgkmcnt(1)
	v_pk_fma_f32 v[48:49], v[74:75], v[30:31], 0 op_sel_hi:[1,0,0]
	v_mov_b32_e32 v23, s4
	v_pk_fma_f32 v[30:31], v[76:77], v[30:31], v[48:49] op_sel:[0,1,0]
	ds_read_b128 v[40:43], v23
	v_pk_fma_f32 v[30:31], v[78:79], v[32:33], v[30:31] op_sel_hi:[1,0,1]
	v_pk_fma_f32 v[30:31], v[98:99], v[32:33], v[30:31] op_sel:[0,1,0]
	s_add_i32 s4, s3, 0x13030
	s_waitcnt lgkmcnt(1)
	v_pk_fma_f32 v[30:31], v[100:101], v[34:35], v[30:31] op_sel_hi:[1,0,1]
	v_mov_b32_e32 v23, s4
	v_pk_fma_f32 v[30:31], v[102:103], v[34:35], v[30:31] op_sel:[0,1,0]
	v_pk_fma_f32 v[30:31], v[104:105], v[36:37], v[30:31] op_sel_hi:[1,0,1]
	ds_read_b128 v[44:47], v23
	v_pk_fma_f32 v[30:31], v[106:107], v[36:37], v[30:31] op_sel:[0,1,0]
	s_waitcnt lgkmcnt(1)
	v_pk_fma_f32 v[30:31], v[108:109], v[40:41], v[30:31] op_sel_hi:[1,0,1]
	v_pk_mul_f32 v[32:33], v[72:73], v[38:39]
	v_pk_fma_f32 v[30:31], v[110:111], v[40:41], v[30:31] op_sel:[0,1,0]
	s_add_i32 s4, s3, 0x13040
	v_pk_fma_f32 v[30:31], v[112:113], v[42:43], v[30:31] op_sel_hi:[1,0,1]
	s_addk_i32 s1, 0x100
	v_pk_fma_f32 v[30:31], v[114:115], v[42:43], v[30:31] op_sel:[0,1,0]
	s_waitcnt lgkmcnt(0)
	v_pk_fma_f32 v[30:31], v[116:117], v[44:45], v[30:31] op_sel_hi:[1,0,1]
	s_nop 0
	v_pk_fma_f32 v[30:31], v[118:119], v[44:45], v[30:31] op_sel:[0,1,0]
	s_nop 0
	v_pk_fma_f32 v[30:31], v[120:121], v[46:47], v[30:31] op_sel_hi:[1,0,1]
	s_nop 0
	v_pk_fma_f32 v[30:31], v[122:123], v[46:47], v[30:31] op_sel:[0,1,0]
	v_pk_fma_f32 v[34:35], v[70:71], v[38:39], v[32:33] op_sel:[0,0,1] op_sel_hi:[1,1,0]
	v_pk_fma_f32 v[32:33], v[70:71], v[38:39], v[32:33] op_sel:[0,0,1] op_sel_hi:[1,1,0] neg_lo:[0,0,1] neg_hi:[0,0,1]
	s_nop 0
	v_mov_b32_e32 v35, v33
	v_pk_add_f32 v[46:47], v[34:35], v[30:31]
	s_nop 0
	v_bfe_u32 v23, v47, 16, 1
	v_add3_u32 v23, v47, v23, s33
	ds_write_b16_d16_hi v22, v23
	v_bfe_u32 v23, v46, 16, 1
	v_add3_u32 v23, v46, v23, s33
	ds_write_b16_d16_hi v22, v23 offset:128
	v_mov_b32_e32 v23, s4
	ds_read_b128 v[30:33], v23
	s_add_i32 s4, s3, 0x13050
	v_mov_b32_e32 v23, s4
	ds_read_b128 v[34:37], v23
	s_add_i32 s4, s3, 0x13060
	s_waitcnt lgkmcnt(1)
	v_pk_fma_f32 v[48:49], v[74:75], v[30:31], 0 op_sel_hi:[1,0,0]
	v_mov_b32_e32 v23, s4
	v_pk_fma_f32 v[30:31], v[76:77], v[30:31], v[48:49] op_sel:[0,1,0]
	ds_read_b128 v[38:41], v23
	v_pk_fma_f32 v[30:31], v[78:79], v[32:33], v[30:31] op_sel_hi:[1,0,1]
	v_pk_fma_f32 v[30:31], v[98:99], v[32:33], v[30:31] op_sel:[0,1,0]
	s_add_i32 s4, s3, 0x13070
	s_waitcnt lgkmcnt(1)
	v_pk_fma_f32 v[30:31], v[100:101], v[34:35], v[30:31] op_sel_hi:[1,0,1]
	v_mov_b32_e32 v23, s4
	v_pk_fma_f32 v[30:31], v[102:103], v[34:35], v[30:31] op_sel:[0,1,0]
	v_pk_fma_f32 v[30:31], v[104:105], v[36:37], v[30:31] op_sel_hi:[1,0,1]
	ds_read_b128 v[42:45], v23
	v_pk_fma_f32 v[30:31], v[106:107], v[36:37], v[30:31] op_sel:[0,1,0]
	s_waitcnt lgkmcnt(1)
	v_pk_fma_f32 v[30:31], v[108:109], v[38:39], v[30:31] op_sel_hi:[1,0,1]
	v_pk_mul_f32 v[32:33], v[72:73], v[46:47]
	v_pk_fma_f32 v[30:31], v[110:111], v[38:39], v[30:31] op_sel:[0,1,0]
	s_add_i32 s4, s3, 0x13080
	v_pk_fma_f32 v[30:31], v[112:113], v[40:41], v[30:31] op_sel_hi:[1,0,1]
	s_nop 0
	v_pk_fma_f32 v[30:31], v[114:115], v[40:41], v[30:31] op_sel:[0,1,0]
	s_waitcnt lgkmcnt(0)
	v_pk_fma_f32 v[30:31], v[116:117], v[42:43], v[30:31] op_sel_hi:[1,0,1]
	s_nop 0
	v_pk_fma_f32 v[30:31], v[118:119], v[42:43], v[30:31] op_sel:[0,1,0]
	s_nop 0
	v_pk_fma_f32 v[30:31], v[120:121], v[44:45], v[30:31] op_sel_hi:[1,0,1]
	s_nop 0
	v_pk_fma_f32 v[30:31], v[122:123], v[44:45], v[30:31] op_sel:[0,1,0]
	v_pk_fma_f32 v[34:35], v[70:71], v[46:47], v[32:33] op_sel:[0,0,1] op_sel_hi:[1,1,0]
	v_pk_fma_f32 v[32:33], v[70:71], v[46:47], v[32:33] op_sel:[0,0,1] op_sel_hi:[1,1,0] neg_lo:[0,0,1] neg_hi:[0,0,1]
	s_nop 0
	v_mov_b32_e32 v35, v33
	v_pk_add_f32 v[46:47], v[34:35], v[30:31]
	s_nop 0
	v_bfe_u32 v23, v47, 16, 1
	v_add3_u32 v23, v47, v23, s33
	ds_write_b16_d16_hi v22, v23 offset:272
	v_bfe_u32 v23, v46, 16, 1
	v_add3_u32 v23, v46, v23, s33
	ds_write_b16_d16_hi v22, v23 offset:400
	v_mov_b32_e32 v23, s4
	ds_read_b128 v[30:33], v23
	s_add_i32 s4, s3, 0x13090
	v_mov_b32_e32 v23, s4
	ds_read_b128 v[34:37], v23
	s_add_i32 s4, s3, 0x130a0
	s_waitcnt lgkmcnt(1)
	v_pk_fma_f32 v[48:49], v[74:75], v[30:31], 0 op_sel_hi:[1,0,0]
	v_mov_b32_e32 v23, s4
	v_pk_fma_f32 v[30:31], v[76:77], v[30:31], v[48:49] op_sel:[0,1,0]
	ds_read_b128 v[38:41], v23
	v_pk_fma_f32 v[30:31], v[78:79], v[32:33], v[30:31] op_sel_hi:[1,0,1]
	v_pk_fma_f32 v[30:31], v[98:99], v[32:33], v[30:31] op_sel:[0,1,0]
	s_add_i32 s4, s3, 0x130b0
	s_waitcnt lgkmcnt(1)
	v_pk_fma_f32 v[30:31], v[100:101], v[34:35], v[30:31] op_sel_hi:[1,0,1]
	v_mov_b32_e32 v23, s4
	v_pk_fma_f32 v[30:31], v[102:103], v[34:35], v[30:31] op_sel:[0,1,0]
	v_pk_fma_f32 v[30:31], v[104:105], v[36:37], v[30:31] op_sel_hi:[1,0,1]
	ds_read_b128 v[42:45], v23
	v_pk_fma_f32 v[30:31], v[106:107], v[36:37], v[30:31] op_sel:[0,1,0]
	s_waitcnt lgkmcnt(1)
	v_pk_fma_f32 v[30:31], v[108:109], v[38:39], v[30:31] op_sel_hi:[1,0,1]
	v_pk_mul_f32 v[32:33], v[72:73], v[46:47]
	v_pk_fma_f32 v[30:31], v[110:111], v[38:39], v[30:31] op_sel:[0,1,0]
	s_add_i32 s4, s3, 0x130c0
	v_pk_fma_f32 v[30:31], v[112:113], v[40:41], v[30:31] op_sel_hi:[1,0,1]
	s_nop 0
	v_pk_fma_f32 v[30:31], v[114:115], v[40:41], v[30:31] op_sel:[0,1,0]
	s_waitcnt lgkmcnt(0)
; #define LAS __attribute__((address_space(3)))
; DI unsigned f2bf(float f) { unsigned u = __builtin_bit_cast(unsigned, f); return (u + 0x7fffu + ((u >> 16) & 1u)) >> 16; }
; DI void ssm_step_lds(const SsmC& c, const LAS bf16_t* up_, float& xr, float& xi) {
;     const LAS f32x4* up = (const LAS f32x4*)up_;
;     const f32x4 u0 = up[0], u1 = up[1], u2 = up[2], u3 = up[3];
;     float sr = 0.f, si = 0.f;
; #pragma unroll
;     for (int e = 0; e < 4; ++e) { sr += c.bbr[e] * u0[e]; si += c.bbi[e] * u0[e]; }
; #pragma unroll
;     for (int e = 0; e < 4; ++e) { sr += c.bbr[4 + e] * u1[e]; si += c.bbi[4 + e] * u1[e]; }
; #pragma unroll
;     for (int e = 0; e < 4; ++e) { sr += c.bbr[8 + e] * u2[e]; si += c.bbi[8 + e] * u2[e]; }
; #pragma unroll
;     for (int e = 0; e < 4; ++e) { sr += c.bbr[12 + e] * u3[e]; si += c.bbi[12 + e] * u3[e]; }
;     const float nxr = c.ar * xr - c.ai * xi + sr, nxi = c.ar * xi + c.ai * xr + si; xr = nxr; xi = nxi;
; }
; DI void ssm_s3(CArgs& a, int l, int it, int lane, LAS bf16_t* Xs  , LAS bf16_t* Us) {
;     ...
;     for (int sub = 0; sub < 4; ++sub) {
; #pragma unroll 4
;         for (int tt = 0; tt < 32; ++tt) { ssm_step_lds(c, Us + (32 * sub + tt) * 32, xr, xi);
;             Xs[tt * 136 + lane] = (bf16_t)f2bf(xr); Xs[tt * 136 + 64 + lane] = (bf16_t)f2bf(xi); }
	v_pk_fma_f32 v[30:31], v[116:117], v[42:43], v[30:31] op_sel_hi:[1,0,1]
	s_nop 0
	v_pk_fma_f32 v[30:31], v[118:119], v[42:43], v[30:31] op_sel:[0,1,0]
	s_nop 0
	v_pk_fma_f32 v[30:31], v[120:121], v[44:45], v[30:31] op_sel_hi:[1,0,1]
	s_nop 0
	v_pk_fma_f32 v[30:31], v[122:123], v[44:45], v[30:31] op_sel:[0,1,0]
	v_pk_fma_f32 v[34:35], v[70:71], v[46:47], v[32:33] op_sel:[0,0,1] op_sel_hi:[1,1,0]
	v_pk_fma_f32 v[32:33], v[70:71], v[46:47], v[32:33] op_sel:[0,0,1] op_sel_hi:[1,1,0] neg_lo:[0,0,1] neg_hi:[0,0,1]
	s_nop 0
	v_mov_b32_e32 v35, v33
	v_pk_add_f32 v[46:47], v[34:35], v[30:31]
	s_nop 0
	v_bfe_u32 v23, v47, 16, 1
	v_add3_u32 v23, v47, v23, s33
	ds_write_b16_d16_hi v22, v23 offset:544
	v_bfe_u32 v23, v46, 16, 1
	v_add3_u32 v23, v46, v23, s33
	ds_write_b16_d16_hi v22, v23 offset:672
	v_mov_b32_e32 v23, s4
	ds_read_b128 v[30:33], v23
	s_add_i32 s4, s3, 0x130d0
	v_mov_b32_e32 v23, s4
	ds_read_b128 v[34:37], v23
	s_add_i32 s4, s3, 0x130e0
	s_waitcnt lgkmcnt(1)
	v_pk_fma_f32 v[48:49], v[74:75], v[30:31], 0 op_sel_hi:[1,0,0]
	v_mov_b32_e32 v23, s4
	v_pk_fma_f32 v[30:31], v[76:77], v[30:31], v[48:49] op_sel:[0,1,0]
	ds_read_b128 v[38:41], v23
	v_pk_fma_f32 v[30:31], v[78:79], v[32:33], v[30:31] op_sel_hi:[1,0,1]
	v_pk_fma_f32 v[30:31], v[98:99], v[32:33], v[30:31] op_sel:[0,1,0]
	s_add_i32 s3, s3, 0x130f0
	s_waitcnt lgkmcnt(1)
	v_pk_fma_f32 v[30:31], v[100:101], v[34:35], v[30:31] op_sel_hi:[1,0,1]
	v_mov_b32_e32 v23, s3
	v_pk_fma_f32 v[30:31], v[102:103], v[34:35], v[30:31] op_sel:[0,1,0]
	v_pk_fma_f32 v[30:31], v[104:105], v[36:37], v[30:31] op_sel_hi:[1,0,1]
	ds_read_b128 v[42:45], v23
	v_pk_fma_f32 v[30:31], v[106:107], v[36:37], v[30:31] op_sel:[0,1,0]
	s_waitcnt lgkmcnt(1)
	v_pk_fma_f32 v[30:31], v[108:109], v[38:39], v[30:31] op_sel_hi:[1,0,1]
	v_pk_mul_f32 v[32:33], v[72:73], v[46:47]
	v_pk_fma_f32 v[30:31], v[110:111], v[38:39], v[30:31] op_sel:[0,1,0]
	s_cmp_lg_u32 s1, 0
	v_pk_fma_f32 v[30:31], v[112:113], v[40:41], v[30:31] op_sel_hi:[1,0,1]
	s_nop 0
	v_pk_fma_f32 v[30:31], v[114:115], v[40:41], v[30:31] op_sel:[0,1,0]
	s_waitcnt lgkmcnt(0)
	v_pk_fma_f32 v[30:31], v[116:117], v[42:43], v[30:31] op_sel_hi:[1,0,1]
	s_nop 0
	v_pk_fma_f32 v[30:31], v[118:119], v[42:43], v[30:31] op_sel:[0,1,0]
	s_nop 0
	v_pk_fma_f32 v[30:31], v[120:121], v[44:45], v[30:31] op_sel_hi:[1,0,1]
	s_nop 0
	v_pk_fma_f32 v[30:31], v[122:123], v[44:45], v[30:31] op_sel:[0,1,0]
	v_pk_fma_f32 v[34:35], v[70:71], v[46:47], v[32:33] op_sel:[0,0,1] op_sel_hi:[1,1,0]
	v_pk_fma_f32 v[32:33], v[70:71], v[46:47], v[32:33] op_sel:[0,0,1] op_sel_hi:[1,1,0] neg_lo:[0,0,1] neg_hi:[0,0,1]
	s_nop 0
	v_mov_b32_e32 v35, v33
	v_pk_add_f32 v[38:39], v[34:35], v[30:31]
	s_nop 0
	v_bfe_u32 v23, v39, 16, 1
	v_add3_u32 v23, v39, v23, s33
	ds_write_b16_d16_hi v22, v23 offset:816
	v_bfe_u32 v23, v38, 16, 1
	v_add3_u32 v23, v38, v23, s33
	ds_write_b16_d16_hi v22, v23 offset:944
	v_add_u32_e32 v22, 0x440, v22
	s_cbranch_scc1 .LBB0_186
; DI unsigned pk2(float lo, float hi) { f32x2 v = {lo, hi}; bf16x2_t b = __builtin_convertvector(v, bf16x2_t); return __builtin_bit_cast(unsigned, b); }
; DI float bflo(unsigned w) { return __uint_as_float(w << 16); }
; DI float bfhi(unsigned w) { return __uint_as_float(w & 0xffff0000u); }
; DI float geluf_(float x) { const float a = 0.7978845608028654f * (x + 0.044715f * x * x * x); const float t = 1.f - 2.f * __builtin_amdgcn_rcpf(__expf(2.f * a) + 1.f); return 0.5f * x * (1.f + t); }
; #define MFMA16(a, b, c) __builtin_amdgcn_mfma_f32_16x16x32_bf16((a), (b), (c), 0, 0, 0)
; DI void ssm_s3(CArgs& a, int l, int it, int lane, LAS bf16_t* Xs  , LAS bf16_t* Us) {
;     ...
; #pragma unroll
;         for (int m = 0; m < 2; ++m) {
;             float zz = 0.f; asm volatile("" : "+v"(zz)); f32x4 acc = {zz, zz, zz, zz};
; #pragma unroll
;             for (int kk = 0; kk < 4; ++kk) { const bf16x8 xf = lds_b128(Xs + (16 * m + fr) * 136 + 32 * kk + 8 * fq); acc = MFMA16(cf[kk], xf, acc); }
;             const size_t tg = t0 + 32 * sub + 16 * m + fr;
;             const u32x2 uw = *(const u32x2*)(zb + tg * NZ + ZU + g * 16 + 4 * fq);
;             const float y0 = geluf_(acc[0] + dsk[0] * bflo(uw.x)), y1 = geluf_(acc[1] + dsk[1] * bfhi(uw.x)), y2 = geluf_(acc[2] + dsk[2] * bflo(uw.y)), y3 = geluf_(acc[3] + dsk[3] * bfhi(uw.y));
;             u32x2 ow; ow.x = pk2(y0, y1); ow.y = pk2(y2, y3);
;             *(u32x2*)(gb + tg * 512 + g * 16 + 4 * fq) = ow;
;         }
;         asm volatile("s_waitcnt lgkmcnt(0)" ::: "memory");
;     }
	v_or_b32_e32 v26, 0x60, v26
	v_mad_u64_u32 v[22:23], s[4:5], v26, s55, v[28:29]
	v_mov_b32_e32 v30, v81
	v_mad_i32_i24 v23, v27, s55, v23
	s_waitcnt lgkmcnt(0)
	ds_read_b128 v[34:37], v126
	v_mov_b32_e32 v31, v30
	v_mov_b32_e32 v32, v30
	v_mov_b32_e32 v33, v30
	v_lshlrev_b64 v[26:27], 10, v[26:27]
	v_lshl_add_u64 v[26:27], v[24:25], 0, v[26:27]
	s_waitcnt lgkmcnt(0)
	v_mfma_f32_16x16x32_bf16 v[30:33], v[4:7], v[34:37], v[30:33]
	ds_read_b128 v[34:37], v126 offset:64
	v_or_b32_e32 v20, 0x1c000, v20
	s_add_i32 s2, s2, s80
	s_waitcnt lgkmcnt(0)
	v_mfma_f32_16x16x32_bf16 v[30:33], v[8:11], v[34:37], v[30:33]
	ds_read_b128 v[34:37], v126 offset:128
	s_cmpk_gt_i32 s2, 0x1fff
	s_waitcnt lgkmcnt(0)
	v_mfma_f32_16x16x32_bf16 v[30:33], v[12:15], v[34:37], v[30:33]
	ds_read_b128 v[34:37], v126 offset:192
	s_waitcnt lgkmcnt(0)
	v_mfma_f32_16x16x32_bf16 v[30:33], v[16:19], v[34:37], v[30:33]
	s_waitcnt vmcnt(1)
	v_mov_b32_e32 v28, v244
	v_mov_b32_e32 v29, v245
	v_lshlrev_b32_e32 v34, 16, v28
	v_and_b32_e32 v35, 0xffff0000, v28
	s_nop 4
	v_pk_fma_f32 v[30:31], v[0:1], v[34:35], v[30:31]
	s_nop 0
	v_mul_f32_e32 v28, 0x3d372713, v30
	v_mul_f32_e32 v28, v30, v28
	v_fma_f32 v28, v30, v28, v30
	v_mul_f32_e32 v28, 0x3f4c422a, v28
	v_add_f32_e32 v28, v28, v28
	v_mul_f32_e32 v28, 0x3fb8aa3b, v28
	v_exp_f32_e32 v28, v28
	s_nop 0
	v_add_f32_e32 v28, 1.0, v28
	v_rcp_f32_e32 v34, v28
	v_mul_f32_e32 v28, 0x3d372713, v31
	v_mul_f32_e32 v28, v31, v28
	v_fma_f32 v28, v31, v28, v31
	v_mul_f32_e32 v28, 0x3f4c422a, v28
	v_add_f32_e32 v28, v28, v28
	v_mul_f32_e32 v28, 0x3fb8aa3b, v28
	v_exp_f32_e32 v28, v28
	v_pk_mul_f32 v[30:31], v[30:31], 0.5 op_sel_hi:[1,0]
	v_add_f32_e32 v28, 1.0, v28
	v_rcp_f32_e32 v35, v28
	v_lshlrev_b32_e32 v28, 16, v29
	v_and_b32_e32 v29, 0xffff0000, v29
	v_pk_fma_f32 v[28:29], v[2:3], v[28:29], v[32:33]
	v_pk_fma_f32 v[34:35], v[34:35], 2.0, 1.0 op_sel_hi:[1,0,0] neg_lo:[1,0,0] neg_hi:[1,0,0]
	v_mul_f32_e32 v32, 0x3d372713, v28
	v_mul_f32_e32 v33, 0x3d372713, v29
	v_mul_f32_e32 v32, v28, v32
	v_mul_f32_e32 v33, v29, v33
	v_fma_f32 v32, v28, v32, v28
	v_fma_f32 v33, v29, v33, v29
	v_mul_f32_e32 v32, 0x3f4c422a, v32
	v_mul_f32_e32 v33, 0x3f4c422a, v33
	v_add_f32_e32 v32, v32, v32
	v_add_f32_e32 v33, v33, v33
	v_mul_f32_e32 v32, 0x3fb8aa3b, v32
	v_mul_f32_e32 v33, 0x3fb8aa3b, v33
	v_exp_f32_e32 v32, v32
	v_exp_f32_e32 v33, v33
	v_pk_add_f32 v[34:35], v[34:35], 1.0 op_sel_hi:[1,0]
	v_pk_mul_f32 v[28:29], v[28:29], 0.5 op_sel_hi:[1,0]
	v_add_f32_e32 v32, 1.0, v32
	v_add_f32_e32 v33, 1.0, v33
	v_rcp_f32_e32 v32, v32
	v_rcp_f32_e32 v33, v33
	v_pk_mul_f32 v[30:31], v[30:31], v[34:35]
	v_pk_fma_f32 v[32:33], v[32:33], 2.0, 1.0 op_sel_hi:[1,0,0] neg_lo:[1,0,0] neg_hi:[1,0,0]
	s_nop 0
	v_pk_add_f32 v[32:33], v[32:33], 1.0 op_sel_hi:[1,0]
	v_cvt_pk_bf16_f32 v30, v30, v31
	v_pk_mul_f32 v[28:29], v[28:29], v[32:33]
	s_nop 0
	v_cvt_pk_bf16_f32 v31, v28, v29
	global_store_dwordx2 v[26:27], v[30:31], off
	v_mov_b32_e32 v26, v81
	ds_read_b128 v[30:33], v126 offset:4352
	v_mov_b32_e32 v27, v26
	v_mov_b32_e32 v28, v26
	v_mov_b32_e32 v29, v26
	s_waitcnt lgkmcnt(0)
	s_nop 0
	v_mfma_f32_16x16x32_bf16 v[4:7], v[4:7], v[30:33], v[26:29]
	s_nop 2
	ds_read_b128 v[26:29], v126 offset:4416
	s_waitcnt lgkmcnt(0)
	v_mfma_f32_16x16x32_bf16 v[4:7], v[8:11], v[26:29], v[4:7]
	ds_read_b128 v[8:11], v126 offset:4480
	s_waitcnt lgkmcnt(0)
	v_mfma_f32_16x16x32_bf16 v[4:7], v[12:15], v[8:11], v[4:7]
	ds_read_b128 v[8:11], v126 offset:4544
	s_waitcnt lgkmcnt(0)
	v_mfma_f32_16x16x32_bf16 v[4:7], v[16:19], v[8:11], v[4:7]
	v_add_co_u32_e32 v8, vcc, s79, v22
	s_nop 1
	v_addc_co_u32_e32 v9, vcc, 0, v23, vcc
	s_waitcnt vmcnt(0)
	v_mov_b32_e32 v8, v246
	v_mov_b32_e32 v9, v247
	v_lshlrev_b32_e32 v10, 16, v8
	v_and_b32_e32 v11, 0xffff0000, v8
	v_pk_fma_f32 v[0:1], v[0:1], v[10:11], v[4:5]
	s_nop 0
	v_mul_f32_e32 v4, 0x3d372713, v0
	v_mul_f32_e32 v5, 0x3d372713, v1
	v_mul_f32_e32 v4, v0, v4
	v_mul_f32_e32 v5, v1, v5
	v_fma_f32 v4, v0, v4, v0
	v_fma_f32 v5, v1, v5, v1
	v_mul_f32_e32 v4, 0x3f4c422a, v4
	v_mul_f32_e32 v5, 0x3f4c422a, v5
	v_add_f32_e32 v4, v4, v4
	v_add_f32_e32 v5, v5, v5
	v_mul_f32_e32 v4, 0x3fb8aa3b, v4
	v_mul_f32_e32 v5, 0x3fb8aa3b, v5
	v_exp_f32_e32 v4, v4
	v_exp_f32_e32 v5, v5
	v_pk_mul_f32 v[0:1], v[0:1], 0.5 op_sel_hi:[1,0]
	v_add_f32_e32 v4, 1.0, v4
	v_add_f32_e32 v5, 1.0, v5
	v_rcp_f32_e32 v4, v4
	v_rcp_f32_e32 v5, v5
	s_nop 0
	v_pk_fma_f32 v[4:5], v[4:5], 2.0, 1.0 op_sel_hi:[1,0,0] neg_lo:[1,0,0] neg_hi:[1,0,0]
	s_nop 0
	v_pk_add_f32 v[4:5], v[4:5], 1.0 op_sel_hi:[1,0]
	s_nop 0
	v_pk_mul_f32 v[0:1], v[0:1], v[4:5]
	v_lshlrev_b32_e32 v4, 16, v9
	v_and_b32_e32 v5, 0xffff0000, v9
	v_pk_fma_f32 v[2:3], v[2:3], v[4:5], v[6:7]
	v_cvt_pk_bf16_f32 v0, v0, v1
	v_mul_f32_e32 v4, 0x3d372713, v2
	v_mul_f32_e32 v5, 0x3d372713, v3
	v_mul_f32_e32 v4, v2, v4
	v_mul_f32_e32 v5, v3, v5
	v_fma_f32 v4, v2, v4, v2
	v_fma_f32 v5, v3, v5, v3
	v_mul_f32_e32 v4, 0x3f4c422a, v4
	v_mul_f32_e32 v5, 0x3f4c422a, v5
	v_add_f32_e32 v4, v4, v4
	v_add_f32_e32 v5, v5, v5
	v_mul_f32_e32 v4, 0x3fb8aa3b, v4
	v_mul_f32_e32 v5, 0x3fb8aa3b, v5
	v_exp_f32_e32 v4, v4
	v_exp_f32_e32 v5, v5
	v_pk_mul_f32 v[2:3], v[2:3], 0.5 op_sel_hi:[1,0]
	v_add_f32_e32 v4, 1.0, v4
	v_add_f32_e32 v5, 1.0, v5
	v_rcp_f32_e32 v4, v4
	v_rcp_f32_e32 v5, v5
	s_nop 0
	v_pk_fma_f32 v[4:5], v[4:5], 2.0, 1.0 op_sel_hi:[1,0,0] neg_lo:[1,0,0] neg_hi:[1,0,0]
	s_nop 0
	v_pk_add_f32 v[4:5], v[4:5], 1.0 op_sel_hi:[1,0]
	s_nop 0
	v_pk_mul_f32 v[2:3], v[2:3], v[4:5]
	s_nop 0
	v_cvt_pk_bf16_f32 v1, v2, v3
	v_lshl_add_u64 v[2:3], v[24:25], 0, v[20:21]
	global_store_dwordx2 v[2:3], v[0:1], off
	s_waitcnt lgkmcnt(0)
	s_cbranch_scc0 .LBB0_179

; #define LAS __attribute__((address_space(3)))
; DI void ssm_step_lds(const SsmC& c, const LAS bf16_t* up_, float& xr, float& xi) {
;     const LAS f32x4* up = (const LAS f32x4*)up_;
;     const f32x4 u0 = up[0], u1 = up[1], u2 = up[2], u3 = up[3];
;     float sr = 0.f, si = 0.f;
; #pragma unroll
;     for (int e = 0; e < 4; ++e) { sr += c.bbr[e] * u0[e]; si += c.bbi[e] * u0[e]; }
; #pragma unroll
;     for (int e = 0; e < 4; ++e) { sr += c.bbr[4 + e] * u1[e]; si += c.bbi[4 + e] * u1[e]; }
; #pragma unroll
;     for (int e = 0; e < 4; ++e) { sr += c.bbr[8 + e] * u2[e]; si += c.bbi[8 + e] * u2[e]; }
; #pragma unroll
;     for (int e = 0; e < 4; ++e) { sr += c.bbr[12 + e] * u3[e]; si += c.bbi[12 + e] * u3[e]; }
;     const float nxr = c.ar * xr - c.ai * xi + sr, nxi = c.ar * xi + c.ai * xr + si; xr = nxr; xi = nxi;
; }
; DI void ssm_s1(CArgs& a, int l, int it, int lane, LAS bf16_t* Us) {
;     ...
; #pragma unroll 4
;     for (int t = 0; t < 128; ++t) ssm_step_lds(c, Us + t * 32, xr, xi);
;     asm volatile("s_waitcnt lgkmcnt(0)" ::: "memory");
;     ((f32x2*)(a.ws + WS_XLOC))[(size_t)it * 64 + lane] = (f32x2){xr, xi};
.LBB0_443:
	s_add_i32 s1, s4, s0
	v_mov_b32_e32 v35, s1
	ds_read_b128 v[0:3], v35
	ds_read_b128 v[4:7], v35 offset:16
	ds_read_b128 v[8:11], v35 offset:32
	ds_read_b128 v[12:15], v35 offset:48
	s_addk_i32 s0, 0x100
	s_waitcnt lgkmcnt(3)
	v_pk_fma_f32 v[76:77], v[42:43], v[0:1], 0 op_sel_hi:[1,0,0]
	s_cmpk_lg_i32 s0, 0x2000
	v_pk_fma_f32 v[0:1], v[44:45], v[0:1], v[76:77] op_sel:[0,1,0]
	s_nop 0
	v_pk_fma_f32 v[0:1], v[46:47], v[2:3], v[0:1] op_sel_hi:[1,0,1]
	v_pk_fma_f32 v[0:1], v[48:49], v[2:3], v[0:1] op_sel:[0,1,0]
	v_pk_mul_f32 v[2:3], v[38:39], v[40:41] op_sel:[0,1] op_sel_hi:[1,0]
	s_waitcnt lgkmcnt(2)
	v_pk_fma_f32 v[0:1], v[50:51], v[4:5], v[0:1] op_sel_hi:[1,0,1]
	s_nop 0
	v_pk_fma_f32 v[0:1], v[52:53], v[4:5], v[0:1] op_sel:[0,1,0]
	v_pk_fma_f32 v[0:1], v[54:55], v[6:7], v[0:1] op_sel_hi:[1,0,1]
	s_nop 0
	v_pk_fma_f32 v[0:1], v[56:57], v[6:7], v[0:1] op_sel:[0,1,0]
	s_waitcnt lgkmcnt(1)
	v_pk_fma_f32 v[0:1], v[58:59], v[8:9], v[0:1] op_sel_hi:[1,0,1]
	s_nop 0
	v_pk_fma_f32 v[0:1], v[60:61], v[8:9], v[0:1] op_sel:[0,1,0]
	s_nop 0
	v_pk_fma_f32 v[0:1], v[62:63], v[10:11], v[0:1] op_sel_hi:[1,0,1]
	s_nop 0
	v_pk_fma_f32 v[0:1], v[64:65], v[10:11], v[0:1] op_sel:[0,1,0]
	s_waitcnt lgkmcnt(0)
	v_pk_fma_f32 v[0:1], v[66:67], v[12:13], v[0:1] op_sel_hi:[1,0,1]
	s_nop 0
	v_pk_fma_f32 v[0:1], v[68:69], v[12:13], v[0:1] op_sel:[0,1,0]
	s_nop 0
	v_pk_fma_f32 v[0:1], v[70:71], v[14:15], v[0:1] op_sel_hi:[1,0,1]
	s_nop 0
	v_pk_fma_f32 v[0:1], v[72:73], v[14:15], v[0:1] op_sel:[0,1,0]
	v_pk_fma_f32 v[4:5], v[36:37], v[40:41], v[2:3] neg_lo:[0,0,1] neg_hi:[0,0,1]
	v_pk_fma_f32 v[2:3], v[36:37], v[40:41], v[2:3]
	s_nop 0
	v_mov_b32_e32 v5, v3
	v_pk_add_f32 v[40:41], v[4:5], v[0:1]
	ds_read_b128 v[0:3], v35 offset:64
	ds_read_b128 v[4:7], v35 offset:80
	ds_read_b128 v[8:11], v35 offset:96
	ds_read_b128 v[12:15], v35 offset:112
	s_waitcnt lgkmcnt(3)
	v_pk_fma_f32 v[76:77], v[42:43], v[0:1], 0 op_sel_hi:[1,0,0]
	s_nop 0
	v_pk_fma_f32 v[0:1], v[44:45], v[0:1], v[76:77] op_sel:[0,1,0]
	s_nop 0
	v_pk_fma_f32 v[0:1], v[46:47], v[2:3], v[0:1] op_sel_hi:[1,0,1]
	v_pk_fma_f32 v[0:1], v[48:49], v[2:3], v[0:1] op_sel:[0,1,0]
	v_pk_mul_f32 v[2:3], v[38:39], v[40:41] op_sel:[0,1] op_sel_hi:[1,0]
	s_waitcnt lgkmcnt(2)
	v_pk_fma_f32 v[0:1], v[50:51], v[4:5], v[0:1] op_sel_hi:[1,0,1]
	s_nop 0
	v_pk_fma_f32 v[0:1], v[52:53], v[4:5], v[0:1] op_sel:[0,1,0]
	v_pk_fma_f32 v[0:1], v[54:55], v[6:7], v[0:1] op_sel_hi:[1,0,1]
	s_nop 0
	v_pk_fma_f32 v[0:1], v[56:57], v[6:7], v[0:1] op_sel:[0,1,0]
	s_waitcnt lgkmcnt(1)
	v_pk_fma_f32 v[0:1], v[58:59], v[8:9], v[0:1] op_sel_hi:[1,0,1]
	s_nop 0
	v_pk_fma_f32 v[0:1], v[60:61], v[8:9], v[0:1] op_sel:[0,1,0]
	s_nop 0
	v_pk_fma_f32 v[0:1], v[62:63], v[10:11], v[0:1] op_sel_hi:[1,0,1]
	s_nop 0
	v_pk_fma_f32 v[0:1], v[64:65], v[10:11], v[0:1] op_sel:[0,1,0]
	s_waitcnt lgkmcnt(0)
	v_pk_fma_f32 v[0:1], v[66:67], v[12:13], v[0:1] op_sel_hi:[1,0,1]
	s_nop 0
	v_pk_fma_f32 v[0:1], v[68:69], v[12:13], v[0:1] op_sel:[0,1,0]
	s_nop 0
	v_pk_fma_f32 v[0:1], v[70:71], v[14:15], v[0:1] op_sel_hi:[1,0,1]
	s_nop 0
	v_pk_fma_f32 v[0:1], v[72:73], v[14:15], v[0:1] op_sel:[0,1,0]
	v_pk_fma_f32 v[4:5], v[36:37], v[40:41], v[2:3] neg_lo:[0,0,1] neg_hi:[0,0,1]
	v_pk_fma_f32 v[2:3], v[36:37], v[40:41], v[2:3]
	s_nop 0
	v_mov_b32_e32 v5, v3
	v_pk_add_f32 v[40:41], v[4:5], v[0:1]
	ds_read_b128 v[0:3], v35 offset:128
	ds_read_b128 v[4:7], v35 offset:144
	ds_read_b128 v[8:11], v35 offset:160
	ds_read_b128 v[12:15], v35 offset:176
	s_waitcnt lgkmcnt(3)
	v_pk_fma_f32 v[76:77], v[42:43], v[0:1], 0 op_sel_hi:[1,0,0]
	s_nop 0
	v_pk_fma_f32 v[0:1], v[44:45], v[0:1], v[76:77] op_sel:[0,1,0]
	s_nop 0
	v_pk_fma_f32 v[0:1], v[46:47], v[2:3], v[0:1] op_sel_hi:[1,0,1]
	v_pk_fma_f32 v[0:1], v[48:49], v[2:3], v[0:1] op_sel:[0,1,0]
	v_pk_mul_f32 v[2:3], v[38:39], v[40:41] op_sel:[0,1] op_sel_hi:[1,0]
	s_waitcnt lgkmcnt(2)
	v_pk_fma_f32 v[0:1], v[50:51], v[4:5], v[0:1] op_sel_hi:[1,0,1]
	s_nop 0
	v_pk_fma_f32 v[0:1], v[52:53], v[4:5], v[0:1] op_sel:[0,1,0]
	v_pk_fma_f32 v[0:1], v[54:55], v[6:7], v[0:1] op_sel_hi:[1,0,1]
	s_nop 0
	v_pk_fma_f32 v[0:1], v[56:57], v[6:7], v[0:1] op_sel:[0,1,0]
	s_waitcnt lgkmcnt(1)
	v_pk_fma_f32 v[0:1], v[58:59], v[8:9], v[0:1] op_sel_hi:[1,0,1]
	s_nop 0
	v_pk_fma_f32 v[0:1], v[60:61], v[8:9], v[0:1] op_sel:[0,1,0]
	s_nop 0
	v_pk_fma_f32 v[0:1], v[62:63], v[10:11], v[0:1] op_sel_hi:[1,0,1]
	s_nop 0
	v_pk_fma_f32 v[0:1], v[64:65], v[10:11], v[0:1] op_sel:[0,1,0]
	s_waitcnt lgkmcnt(0)
	v_pk_fma_f32 v[0:1], v[66:67], v[12:13], v[0:1] op_sel_hi:[1,0,1]
	s_nop 0
	v_pk_fma_f32 v[0:1], v[68:69], v[12:13], v[0:1] op_sel:[0,1,0]
	s_nop 0
	v_pk_fma_f32 v[0:1], v[70:71], v[14:15], v[0:1] op_sel_hi:[1,0,1]
	s_nop 0
	v_pk_fma_f32 v[0:1], v[72:73], v[14:15], v[0:1] op_sel:[0,1,0]
	v_pk_fma_f32 v[4:5], v[36:37], v[40:41], v[2:3] neg_lo:[0,0,1] neg_hi:[0,0,1]
	v_pk_fma_f32 v[2:3], v[36:37], v[40:41], v[2:3]
	s_nop 0
	v_mov_b32_e32 v5, v3
	v_pk_add_f32 v[40:41], v[4:5], v[0:1]
	ds_read_b128 v[0:3], v35 offset:192
	ds_read_b128 v[4:7], v35 offset:208
	ds_read_b128 v[8:11], v35 offset:224
	ds_read_b128 v[12:15], v35 offset:240
	s_waitcnt lgkmcnt(3)
	v_pk_fma_f32 v[76:77], v[42:43], v[0:1], 0 op_sel_hi:[1,0,0]
	s_nop 0
	v_pk_fma_f32 v[0:1], v[44:45], v[0:1], v[76:77] op_sel:[0,1,0]
	s_nop 0
	v_pk_fma_f32 v[0:1], v[46:47], v[2:3], v[0:1] op_sel_hi:[1,0,1]
	v_pk_fma_f32 v[0:1], v[48:49], v[2:3], v[0:1] op_sel:[0,1,0]
	v_pk_mul_f32 v[2:3], v[38:39], v[40:41] op_sel:[0,1] op_sel_hi:[1,0]
	s_waitcnt lgkmcnt(2)
	v_pk_fma_f32 v[0:1], v[50:51], v[4:5], v[0:1] op_sel_hi:[1,0,1]
	s_nop 0
	v_pk_fma_f32 v[0:1], v[52:53], v[4:5], v[0:1] op_sel:[0,1,0]
	v_pk_fma_f32 v[0:1], v[54:55], v[6:7], v[0:1] op_sel_hi:[1,0,1]
	s_nop 0
	v_pk_fma_f32 v[0:1], v[56:57], v[6:7], v[0:1] op_sel:[0,1,0]
	s_waitcnt lgkmcnt(1)
	v_pk_fma_f32 v[0:1], v[58:59], v[8:9], v[0:1] op_sel_hi:[1,0,1]
	s_nop 0
	v_pk_fma_f32 v[0:1], v[60:61], v[8:9], v[0:1] op_sel:[0,1,0]
	s_nop 0
	v_pk_fma_f32 v[0:1], v[62:63], v[10:11], v[0:1] op_sel_hi:[1,0,1]
	s_nop 0
	v_pk_fma_f32 v[0:1], v[64:65], v[10:11], v[0:1] op_sel:[0,1,0]
	s_waitcnt lgkmcnt(0)
	v_pk_fma_f32 v[0:1], v[66:67], v[12:13], v[0:1] op_sel_hi:[1,0,1]
	s_nop 0
	v_pk_fma_f32 v[0:1], v[68:69], v[12:13], v[0:1] op_sel:[0,1,0]
	s_nop 0
	v_pk_fma_f32 v[0:1], v[70:71], v[14:15], v[0:1] op_sel_hi:[1,0,1]
	s_nop 0
	v_pk_fma_f32 v[0:1], v[72:73], v[14:15], v[0:1] op_sel:[0,1,0]
	v_pk_fma_f32 v[4:5], v[36:37], v[40:41], v[2:3] neg_lo:[0,0,1] neg_hi:[0,0,1]
	v_pk_fma_f32 v[2:3], v[36:37], v[40:41], v[2:3]
	s_nop 0
	v_mov_b32_e32 v5, v3
	v_pk_add_f32 v[40:41], v[4:5], v[0:1]
	s_cbranch_scc1 .LBB0_443
	s_waitcnt lgkmcnt(0)
	s_ashr_i32 s17, s16, 31
	s_lshl_b64 s[0:1], s[16:17], 9
	s_add_i32 s16, s16, s80
	v_lshl_add_u64 v[0:1], v[32:33], 0, s[0:1]
	s_cmpk_gt_i32 s16, 0x1fff
	global_store_dwordx2 v[0:1], v[40:41], off
	s_cbranch_scc0 .LBB0_442
